# ffup tail: last 128 tiles run as 256 half tiles (64x128, swapped-operand 128x64 K-loop) on workgroups 0..255 instead of a ninth round of full tiles
# speedup vs baseline: 1.0005x; 1.0005x over previous
.LBB0_1034:
	v_lshl_or_b32 v115, v183, 3, v191
	v_lshrrev_b32_e32 v116, 6, v115
	v_and_b32_e32 v117, 63, v115
	v_lshlrev_b32_e32 v113, 11, v116
	v_add_u32_e32 v113, 0x10000, v113
	v_readfirstlane_b32 s100, v116
	v_and_b32_e32 v112, 31, v117
	v_lshl_add_u32 v112, v112, 1, v113
	v_lshrrev_b32_e32 v116, 5, v117
	v_lshl_add_u32 v112, v116, 8, v112
	v_lshl_add_u32 v113, v117, 4, v113
	v_lshrrev_b32_e32 v116, 2, v117
	v_mul_u32_u24_e32 v116, 0x1600, v116
	v_and_b32_e32 v114, 3, v117
	v_lshl_add_u32 v114, v114, 4, v116
	s_lshr_b32 s101, s100, 1
	s_lshl_b32 s101, s101, 6
	s_add_u32 s101, s101, s48
	s_mul_i32 s101, s101, 0x1600
	s_and_b32 s100, s100, 1
	s_lshl_b32 s100, s100, 6
	s_add_u32 s100, s100, s49
	s_add_u32 s101, s101, s100
	s_add_u32 s98, s90, 0x3971900
	s_addc_u32 s99, s91, 0
	s_add_u32 s98, s98, s101
	s_addc_u32 s99, s99, 0
	v_mul_f32_e32 v64, 0xbfb8aa3b, v48
	v_mul_f32_e32 v70, 0xbfb8aa3b, v49
	v_mul_f32_e32 v76, 0xbfb8aa3b, v50
	v_mul_f32_e32 v82, 0xbfb8aa3b, v51
	v_exp_f32_e32 v64, v64
	v_exp_f32_e32 v70, v70
	v_exp_f32_e32 v76, v76
	v_exp_f32_e32 v82, v82
	v_add_f32_e32 v64, 1.0, v64
	v_add_f32_e32 v70, 1.0, v70
	v_add_f32_e32 v76, 1.0, v76
	v_add_f32_e32 v82, 1.0, v82
	v_div_scale_f32 v65, s[2:3], v64, v64, 1.0
	v_div_scale_f32 v71, s[2:3], v70, v70, 1.0
	v_div_scale_f32 v77, s[2:3], v76, v76, 1.0
	v_div_scale_f32 v83, s[2:3], v82, v82, 1.0
	v_rcp_f32_e32 v66, v65
	v_rcp_f32_e32 v72, v71
	v_rcp_f32_e32 v78, v77
	v_rcp_f32_e32 v84, v83
	v_fma_f32 v69, -v65, v66, 1.0
	v_fma_f32 v75, -v71, v72, 1.0
	v_fma_f32 v81, -v77, v78, 1.0
	v_fma_f32 v87, -v83, v84, 1.0
	v_fmac_f32_e32 v66, v69, v66
	v_fmac_f32_e32 v72, v75, v72
	v_fmac_f32_e32 v78, v81, v78
	v_fmac_f32_e32 v84, v87, v84
	v_div_scale_f32 v67, vcc, 1.0, v64, 1.0
	v_mul_f32_e32 v88, 0xbfb8aa3b, v52
	v_mul_f32_e32 v68, v67, v66
	v_mul_f32_e32 v94, 0xbfb8aa3b, v53
	v_fma_f32 v69, -v65, v68, v67
	v_mul_f32_e32 v100, 0xbfb8aa3b, v54
	v_fmac_f32_e32 v68, v69, v66
	v_mul_f32_e32 v106, 0xbfb8aa3b, v55
	v_fma_f32 v65, -v65, v68, v67
	v_exp_f32_e32 v88, v88
	v_div_fmas_f32 v65, v65, v66, v68
	v_exp_f32_e32 v94, v94
	v_div_scale_f32 v73, vcc, 1.0, v70, 1.0
	v_exp_f32_e32 v100, v100
	v_mul_f32_e32 v74, v73, v72
	v_exp_f32_e32 v106, v106
	v_fma_f32 v75, -v71, v74, v73
	v_add_f32_e32 v88, 1.0, v88
	v_fmac_f32_e32 v74, v75, v72
	v_add_f32_e32 v94, 1.0, v94
	v_fma_f32 v71, -v71, v74, v73
	v_add_f32_e32 v100, 1.0, v100
	v_div_fmas_f32 v71, v71, v72, v74
	v_add_f32_e32 v106, 1.0, v106
	v_div_scale_f32 v79, vcc, 1.0, v76, 1.0
	v_div_scale_f32 v89, s[2:3], v88, v88, 1.0
	v_mul_f32_e32 v80, v79, v78
	v_div_scale_f32 v95, s[2:3], v94, v94, 1.0
	v_fma_f32 v81, -v77, v80, v79
	v_div_scale_f32 v101, s[2:3], v100, v100, 1.0
	v_fmac_f32_e32 v80, v81, v78
	v_div_scale_f32 v107, s[2:3], v106, v106, 1.0
	v_fma_f32 v77, -v77, v80, v79
	v_rcp_f32_e32 v90, v89
	v_div_fmas_f32 v77, v77, v78, v80
	v_rcp_f32_e32 v96, v95
	v_div_scale_f32 v85, vcc, 1.0, v82, 1.0
	v_rcp_f32_e32 v102, v101
	v_mul_f32_e32 v86, v85, v84
	v_rcp_f32_e32 v108, v107
	v_fma_f32 v87, -v83, v86, v85
	v_fma_f32 v93, -v89, v90, 1.0
	v_fmac_f32_e32 v86, v87, v84
	v_fma_f32 v99, -v95, v96, 1.0
	v_fma_f32 v83, -v83, v86, v85
	v_fma_f32 v105, -v101, v102, 1.0
	v_div_fmas_f32 v83, v83, v84, v86
	v_fma_f32 v111, -v107, v108, 1.0
	v_fmac_f32_e32 v90, v93, v90
	v_fmac_f32_e32 v96, v99, v96
	v_fmac_f32_e32 v102, v105, v102
	v_fmac_f32_e32 v108, v111, v108
	v_div_fixup_f32 v65, v65, v64, 1.0
	v_div_fixup_f32 v71, v71, v70, 1.0
	v_div_fixup_f32 v77, v77, v76, 1.0
	v_div_fixup_f32 v83, v83, v82, 1.0
	v_mul_f32_e32 v65, v48, v65
	v_mul_f32_e32 v71, v49, v71
	v_mul_f32_e32 v77, v50, v77
	v_mul_f32_e32 v83, v51, v83
	v_mul_f32_e32 v65, v32, v65
	v_mul_f32_e32 v71, v33, v71
	v_mul_f32_e32 v77, v34, v77
	v_mul_f32_e32 v83, v35, v83
	v_cvt_pk_bf16_f32 v65, v65, v65
	v_cvt_pk_bf16_f32 v71, v71, v71
	v_cvt_pk_bf16_f32 v77, v77, v77
	v_cvt_pk_bf16_f32 v83, v83, v83
	ds_write_b16 v112, v65
	ds_write_b16 v112, v71 offset:64
	ds_write_b16 v112, v77 offset:128
	ds_write_b16 v112, v83 offset:192
	v_div_scale_f32 v91, vcc, 1.0, v88, 1.0
	v_mul_f32_e32 v64, 0xbfb8aa3b, v56
	v_mul_f32_e32 v92, v91, v90
	v_mul_f32_e32 v70, 0xbfb8aa3b, v57
	v_fma_f32 v93, -v89, v92, v91
	v_mul_f32_e32 v76, 0xbfb8aa3b, v58
	v_fmac_f32_e32 v92, v93, v90
	v_mul_f32_e32 v82, 0xbfb8aa3b, v59
	v_fma_f32 v89, -v89, v92, v91
	v_exp_f32_e32 v64, v64
	v_div_fmas_f32 v89, v89, v90, v92
	v_exp_f32_e32 v70, v70
	v_div_scale_f32 v97, vcc, 1.0, v94, 1.0
	v_exp_f32_e32 v76, v76
	v_mul_f32_e32 v98, v97, v96
	v_exp_f32_e32 v82, v82
	v_fma_f32 v99, -v95, v98, v97
	v_add_f32_e32 v64, 1.0, v64
	v_fmac_f32_e32 v98, v99, v96
	v_add_f32_e32 v70, 1.0, v70
	v_fma_f32 v95, -v95, v98, v97
	v_add_f32_e32 v76, 1.0, v76
	v_div_fmas_f32 v95, v95, v96, v98
	v_add_f32_e32 v82, 1.0, v82
	v_div_scale_f32 v103, vcc, 1.0, v100, 1.0
	v_div_scale_f32 v65, s[2:3], v64, v64, 1.0
	v_mul_f32_e32 v104, v103, v102
	v_div_scale_f32 v71, s[2:3], v70, v70, 1.0
	v_fma_f32 v105, -v101, v104, v103
	v_div_scale_f32 v77, s[2:3], v76, v76, 1.0
	v_fmac_f32_e32 v104, v105, v102
	v_div_scale_f32 v83, s[2:3], v82, v82, 1.0
	v_fma_f32 v101, -v101, v104, v103
	v_rcp_f32_e32 v66, v65
	v_div_fmas_f32 v101, v101, v102, v104
	v_rcp_f32_e32 v72, v71
	v_div_scale_f32 v109, vcc, 1.0, v106, 1.0
	v_rcp_f32_e32 v78, v77
	v_mul_f32_e32 v110, v109, v108
	v_rcp_f32_e32 v84, v83
	v_fma_f32 v111, -v107, v110, v109
	v_fma_f32 v69, -v65, v66, 1.0
	v_fmac_f32_e32 v110, v111, v108
	v_fma_f32 v75, -v71, v72, 1.0
	v_fma_f32 v107, -v107, v110, v109
	v_fma_f32 v81, -v77, v78, 1.0
	v_div_fmas_f32 v107, v107, v108, v110
	v_fma_f32 v87, -v83, v84, 1.0
	v_fmac_f32_e32 v66, v69, v66
	v_fmac_f32_e32 v72, v75, v72
	v_fmac_f32_e32 v78, v81, v78
	v_fmac_f32_e32 v84, v87, v84
	v_div_fixup_f32 v89, v89, v88, 1.0
	v_div_fixup_f32 v95, v95, v94, 1.0
	v_div_fixup_f32 v101, v101, v100, 1.0
	v_div_fixup_f32 v107, v107, v106, 1.0
	v_mul_f32_e32 v89, v52, v89
	v_mul_f32_e32 v95, v53, v95
	v_mul_f32_e32 v101, v54, v101
	v_mul_f32_e32 v107, v55, v107
	v_mul_f32_e32 v89, v36, v89
	v_mul_f32_e32 v95, v37, v95
	v_mul_f32_e32 v101, v38, v101
	v_mul_f32_e32 v107, v39, v107
	v_cvt_pk_bf16_f32 v89, v89, v89
	v_cvt_pk_bf16_f32 v95, v95, v95
	v_cvt_pk_bf16_f32 v101, v101, v101
	v_cvt_pk_bf16_f32 v107, v107, v107
	ds_write_b16 v112, v89 offset:512
	ds_write_b16 v112, v95 offset:576
	ds_write_b16 v112, v101 offset:640
	ds_write_b16 v112, v107 offset:704
	v_div_scale_f32 v67, vcc, 1.0, v64, 1.0
	v_mul_f32_e32 v88, 0xbfb8aa3b, v60
	v_mul_f32_e32 v68, v67, v66
	v_mul_f32_e32 v94, 0xbfb8aa3b, v61
	v_fma_f32 v69, -v65, v68, v67
	v_mul_f32_e32 v100, 0xbfb8aa3b, v62
	v_fmac_f32_e32 v68, v69, v66
	v_mul_f32_e32 v106, 0xbfb8aa3b, v63
	v_fma_f32 v65, -v65, v68, v67
	v_exp_f32_e32 v88, v88
	v_div_fmas_f32 v65, v65, v66, v68
	v_exp_f32_e32 v94, v94
	v_div_scale_f32 v73, vcc, 1.0, v70, 1.0
	v_exp_f32_e32 v100, v100
	v_mul_f32_e32 v74, v73, v72
	v_exp_f32_e32 v106, v106
	v_fma_f32 v75, -v71, v74, v73
	v_add_f32_e32 v88, 1.0, v88
	v_fmac_f32_e32 v74, v75, v72
	v_add_f32_e32 v94, 1.0, v94
	v_fma_f32 v71, -v71, v74, v73
	v_add_f32_e32 v100, 1.0, v100
	v_div_fmas_f32 v71, v71, v72, v74
	v_add_f32_e32 v106, 1.0, v106
	v_div_scale_f32 v79, vcc, 1.0, v76, 1.0
	v_div_scale_f32 v89, s[2:3], v88, v88, 1.0
	v_mul_f32_e32 v80, v79, v78
	v_div_scale_f32 v95, s[2:3], v94, v94, 1.0
	v_fma_f32 v81, -v77, v80, v79
	v_div_scale_f32 v101, s[2:3], v100, v100, 1.0
	v_fmac_f32_e32 v80, v81, v78
	v_div_scale_f32 v107, s[2:3], v106, v106, 1.0
	v_fma_f32 v77, -v77, v80, v79
	v_rcp_f32_e32 v90, v89
	v_div_fmas_f32 v77, v77, v78, v80
	v_rcp_f32_e32 v96, v95
	v_div_scale_f32 v85, vcc, 1.0, v82, 1.0
	v_rcp_f32_e32 v102, v101
	v_mul_f32_e32 v86, v85, v84
	v_rcp_f32_e32 v108, v107
	v_fma_f32 v87, -v83, v86, v85
	v_fma_f32 v93, -v89, v90, 1.0
	v_fmac_f32_e32 v86, v87, v84
	v_fma_f32 v99, -v95, v96, 1.0
	v_fma_f32 v83, -v83, v86, v85
	v_fma_f32 v105, -v101, v102, 1.0
	v_div_fmas_f32 v83, v83, v84, v86
	v_fma_f32 v111, -v107, v108, 1.0
	v_fmac_f32_e32 v90, v93, v90
	v_fmac_f32_e32 v96, v99, v96
	v_fmac_f32_e32 v102, v105, v102
	v_fmac_f32_e32 v108, v111, v108
	v_div_fixup_f32 v65, v65, v64, 1.0
	v_div_fixup_f32 v71, v71, v70, 1.0
	v_div_fixup_f32 v77, v77, v76, 1.0
	v_div_fixup_f32 v83, v83, v82, 1.0
	v_mul_f32_e32 v65, v56, v65
	v_mul_f32_e32 v71, v57, v71
	v_mul_f32_e32 v77, v58, v77
	v_mul_f32_e32 v83, v59, v83
	v_mul_f32_e32 v65, v40, v65
	v_mul_f32_e32 v71, v41, v71
	v_mul_f32_e32 v77, v42, v77
	v_mul_f32_e32 v83, v43, v83
	v_cvt_pk_bf16_f32 v65, v65, v65
	v_cvt_pk_bf16_f32 v71, v71, v71
	v_cvt_pk_bf16_f32 v77, v77, v77
	v_cvt_pk_bf16_f32 v83, v83, v83
	ds_write_b16 v112, v65 offset:1024
	ds_write_b16 v112, v71 offset:1088
	ds_write_b16 v112, v77 offset:1152
	ds_write_b16 v112, v83 offset:1216
	v_div_scale_f32 v91, vcc, 1.0, v88, 1.0
	v_mul_f32_e32 v64, 0xbfb8aa3b, v16
	v_mul_f32_e32 v92, v91, v90
	v_mul_f32_e32 v70, 0xbfb8aa3b, v17
	v_fma_f32 v93, -v89, v92, v91
	v_mul_f32_e32 v76, 0xbfb8aa3b, v18
	v_fmac_f32_e32 v92, v93, v90
	v_mul_f32_e32 v82, 0xbfb8aa3b, v19
	v_fma_f32 v89, -v89, v92, v91
	v_exp_f32_e32 v64, v64
	v_div_fmas_f32 v89, v89, v90, v92
	v_exp_f32_e32 v70, v70
	v_div_scale_f32 v97, vcc, 1.0, v94, 1.0
	v_exp_f32_e32 v76, v76
	v_mul_f32_e32 v98, v97, v96
	v_exp_f32_e32 v82, v82
	v_fma_f32 v99, -v95, v98, v97
	v_add_f32_e32 v64, 1.0, v64
	v_fmac_f32_e32 v98, v99, v96
	v_add_f32_e32 v70, 1.0, v70
	v_fma_f32 v95, -v95, v98, v97
	v_add_f32_e32 v76, 1.0, v76
	v_div_fmas_f32 v95, v95, v96, v98
	v_add_f32_e32 v82, 1.0, v82
	v_div_scale_f32 v103, vcc, 1.0, v100, 1.0
	v_div_scale_f32 v65, s[2:3], v64, v64, 1.0
	v_mul_f32_e32 v104, v103, v102
	v_div_scale_f32 v71, s[2:3], v70, v70, 1.0
	v_fma_f32 v105, -v101, v104, v103
	v_div_scale_f32 v77, s[2:3], v76, v76, 1.0
	v_fmac_f32_e32 v104, v105, v102
	v_div_scale_f32 v83, s[2:3], v82, v82, 1.0
	v_fma_f32 v101, -v101, v104, v103
	v_rcp_f32_e32 v66, v65
	v_div_fmas_f32 v101, v101, v102, v104
	v_rcp_f32_e32 v72, v71
	v_div_scale_f32 v109, vcc, 1.0, v106, 1.0
	v_rcp_f32_e32 v78, v77
	v_mul_f32_e32 v110, v109, v108
	v_rcp_f32_e32 v84, v83
	v_fma_f32 v111, -v107, v110, v109
	v_fma_f32 v69, -v65, v66, 1.0
	v_fmac_f32_e32 v110, v111, v108
	v_fma_f32 v75, -v71, v72, 1.0
	v_fma_f32 v107, -v107, v110, v109
	v_fma_f32 v81, -v77, v78, 1.0
	v_div_fmas_f32 v107, v107, v108, v110
	v_fma_f32 v87, -v83, v84, 1.0
	v_fmac_f32_e32 v66, v69, v66
	v_fmac_f32_e32 v72, v75, v72
	v_fmac_f32_e32 v78, v81, v78
	v_fmac_f32_e32 v84, v87, v84
	v_div_fixup_f32 v89, v89, v88, 1.0
	v_div_fixup_f32 v95, v95, v94, 1.0
	v_div_fixup_f32 v101, v101, v100, 1.0
	v_div_fixup_f32 v107, v107, v106, 1.0
	v_mul_f32_e32 v89, v60, v89
	v_mul_f32_e32 v95, v61, v95
	v_mul_f32_e32 v101, v62, v101
	v_mul_f32_e32 v107, v63, v107
	v_mul_f32_e32 v89, v44, v89
	v_mul_f32_e32 v95, v45, v95
	v_mul_f32_e32 v101, v46, v101
	v_mul_f32_e32 v107, v47, v107
	v_cvt_pk_bf16_f32 v89, v89, v89
	v_cvt_pk_bf16_f32 v95, v95, v95
	v_cvt_pk_bf16_f32 v101, v101, v101
	v_cvt_pk_bf16_f32 v107, v107, v107
	ds_write_b16 v112, v89 offset:1536
	ds_write_b16 v112, v95 offset:1600
	ds_write_b16 v112, v101 offset:1664
	ds_write_b16 v112, v107 offset:1728
	ds_read_b128 v[120:123], v113
	ds_read_b128 v[124:127], v113 offset:1024
	v_div_scale_f32 v67, vcc, 1.0, v64, 1.0
	v_mul_f32_e32 v88, 0xbfb8aa3b, v20
	v_mul_f32_e32 v68, v67, v66
	v_mul_f32_e32 v94, 0xbfb8aa3b, v21
	v_fma_f32 v69, -v65, v68, v67
	v_mul_f32_e32 v100, 0xbfb8aa3b, v22
	v_fmac_f32_e32 v68, v69, v66
	v_mul_f32_e32 v106, 0xbfb8aa3b, v23
	v_fma_f32 v65, -v65, v68, v67
	v_exp_f32_e32 v88, v88
	v_div_fmas_f32 v65, v65, v66, v68
	v_exp_f32_e32 v94, v94
	v_div_scale_f32 v73, vcc, 1.0, v70, 1.0
	v_exp_f32_e32 v100, v100
	v_mul_f32_e32 v74, v73, v72
	v_exp_f32_e32 v106, v106
	v_fma_f32 v75, -v71, v74, v73
	v_add_f32_e32 v88, 1.0, v88
	v_fmac_f32_e32 v74, v75, v72
	v_add_f32_e32 v94, 1.0, v94
	v_fma_f32 v71, -v71, v74, v73
	v_add_f32_e32 v100, 1.0, v100
	v_div_fmas_f32 v71, v71, v72, v74
	v_add_f32_e32 v106, 1.0, v106
	v_div_scale_f32 v79, vcc, 1.0, v76, 1.0
	v_div_scale_f32 v89, s[2:3], v88, v88, 1.0
	v_mul_f32_e32 v80, v79, v78
	v_div_scale_f32 v95, s[2:3], v94, v94, 1.0
	v_fma_f32 v81, -v77, v80, v79
	v_div_scale_f32 v101, s[2:3], v100, v100, 1.0
	v_fmac_f32_e32 v80, v81, v78
	v_div_scale_f32 v107, s[2:3], v106, v106, 1.0
	v_fma_f32 v77, -v77, v80, v79
	v_rcp_f32_e32 v90, v89
	v_div_fmas_f32 v77, v77, v78, v80
	v_rcp_f32_e32 v96, v95
	v_div_scale_f32 v85, vcc, 1.0, v82, 1.0
	v_rcp_f32_e32 v102, v101
	v_mul_f32_e32 v86, v85, v84
	v_rcp_f32_e32 v108, v107
	v_fma_f32 v87, -v83, v86, v85
	v_fma_f32 v93, -v89, v90, 1.0
	v_fmac_f32_e32 v86, v87, v84
	v_fma_f32 v99, -v95, v96, 1.0
	v_fma_f32 v83, -v83, v86, v85
	v_fma_f32 v105, -v101, v102, 1.0
	v_div_fmas_f32 v83, v83, v84, v86
	v_fma_f32 v111, -v107, v108, 1.0
	v_fmac_f32_e32 v90, v93, v90
	v_fmac_f32_e32 v96, v99, v96
	v_fmac_f32_e32 v102, v105, v102
	v_fmac_f32_e32 v108, v111, v108
	s_waitcnt lgkmcnt(0)
	global_store_dwordx4 v114, v[120:123], s[98:99]
	s_add_u32 s98, s98, 0x16000
	s_addc_u32 s99, s99, 0
	global_store_dwordx4 v114, v[124:127], s[98:99]
	s_add_u32 s98, s98, 0x16000
	s_addc_u32 s99, s99, 0
	v_div_fixup_f32 v65, v65, v64, 1.0
	v_div_fixup_f32 v71, v71, v70, 1.0
	v_div_fixup_f32 v77, v77, v76, 1.0
	v_div_fixup_f32 v83, v83, v82, 1.0
	v_mul_f32_e32 v65, v16, v65
	v_mul_f32_e32 v71, v17, v71
	v_mul_f32_e32 v77, v18, v77
	v_mul_f32_e32 v83, v19, v83
	v_mul_f32_e32 v65, v0, v65
	v_mul_f32_e32 v71, v1, v71
	v_mul_f32_e32 v77, v2, v77
	v_mul_f32_e32 v83, v3, v83
	v_cvt_pk_bf16_f32 v65, v65, v65
	v_cvt_pk_bf16_f32 v71, v71, v71
	v_cvt_pk_bf16_f32 v77, v77, v77
	v_cvt_pk_bf16_f32 v83, v83, v83
	ds_write_b16 v112, v65
	ds_write_b16 v112, v71 offset:64
	ds_write_b16 v112, v77 offset:128
	ds_write_b16 v112, v83 offset:192
	v_div_scale_f32 v91, vcc, 1.0, v88, 1.0
	v_mul_f32_e32 v64, 0xbfb8aa3b, v24
	v_mul_f32_e32 v92, v91, v90
	v_mul_f32_e32 v70, 0xbfb8aa3b, v25
	v_fma_f32 v93, -v89, v92, v91
	v_mul_f32_e32 v76, 0xbfb8aa3b, v26
	v_fmac_f32_e32 v92, v93, v90
	v_mul_f32_e32 v82, 0xbfb8aa3b, v27
	v_fma_f32 v89, -v89, v92, v91
	v_exp_f32_e32 v64, v64
	v_div_fmas_f32 v89, v89, v90, v92
	v_exp_f32_e32 v70, v70
	v_div_scale_f32 v97, vcc, 1.0, v94, 1.0
	v_exp_f32_e32 v76, v76
	v_mul_f32_e32 v98, v97, v96
	v_exp_f32_e32 v82, v82
	v_fma_f32 v99, -v95, v98, v97
	v_add_f32_e32 v64, 1.0, v64
	v_fmac_f32_e32 v98, v99, v96
	v_add_f32_e32 v70, 1.0, v70
	v_fma_f32 v95, -v95, v98, v97
	v_add_f32_e32 v76, 1.0, v76
	v_div_fmas_f32 v95, v95, v96, v98
	v_add_f32_e32 v82, 1.0, v82
	v_div_scale_f32 v103, vcc, 1.0, v100, 1.0
	v_div_scale_f32 v65, s[2:3], v64, v64, 1.0
	v_mul_f32_e32 v104, v103, v102
	v_div_scale_f32 v71, s[2:3], v70, v70, 1.0
	v_fma_f32 v105, -v101, v104, v103
	v_div_scale_f32 v77, s[2:3], v76, v76, 1.0
	v_fmac_f32_e32 v104, v105, v102
	v_div_scale_f32 v83, s[2:3], v82, v82, 1.0
	v_fma_f32 v101, -v101, v104, v103
	v_rcp_f32_e32 v66, v65
	v_div_fmas_f32 v101, v101, v102, v104
	v_rcp_f32_e32 v72, v71
	v_div_scale_f32 v109, vcc, 1.0, v106, 1.0
	v_rcp_f32_e32 v78, v77
	v_mul_f32_e32 v110, v109, v108
	v_rcp_f32_e32 v84, v83
	v_fma_f32 v111, -v107, v110, v109
	v_fma_f32 v69, -v65, v66, 1.0
	v_fmac_f32_e32 v110, v111, v108
	v_fma_f32 v75, -v71, v72, 1.0
	v_fma_f32 v107, -v107, v110, v109
	v_fma_f32 v81, -v77, v78, 1.0
	v_div_fmas_f32 v107, v107, v108, v110
	v_fma_f32 v87, -v83, v84, 1.0
	v_fmac_f32_e32 v66, v69, v66
	v_fmac_f32_e32 v72, v75, v72
	v_fmac_f32_e32 v78, v81, v78
	v_fmac_f32_e32 v84, v87, v84
	v_div_fixup_f32 v89, v89, v88, 1.0
	v_div_fixup_f32 v95, v95, v94, 1.0
	v_div_fixup_f32 v101, v101, v100, 1.0
	v_div_fixup_f32 v107, v107, v106, 1.0
	v_mul_f32_e32 v89, v20, v89
	v_mul_f32_e32 v95, v21, v95
	v_mul_f32_e32 v101, v22, v101
	v_mul_f32_e32 v107, v23, v107
	v_mul_f32_e32 v89, v4, v89
	v_mul_f32_e32 v95, v5, v95
	v_mul_f32_e32 v101, v6, v101
	v_mul_f32_e32 v107, v7, v107
	v_cvt_pk_bf16_f32 v89, v89, v89
	v_cvt_pk_bf16_f32 v95, v95, v95
	v_cvt_pk_bf16_f32 v101, v101, v101
	v_cvt_pk_bf16_f32 v107, v107, v107
	ds_write_b16 v112, v89 offset:512
	ds_write_b16 v112, v95 offset:576
	ds_write_b16 v112, v101 offset:640
	ds_write_b16 v112, v107 offset:704
	v_div_scale_f32 v67, vcc, 1.0, v64, 1.0
	v_mul_f32_e32 v88, 0xbfb8aa3b, v28
	v_mul_f32_e32 v68, v67, v66
	v_mul_f32_e32 v94, 0xbfb8aa3b, v29
	v_fma_f32 v69, -v65, v68, v67
	v_mul_f32_e32 v100, 0xbfb8aa3b, v30
	v_fmac_f32_e32 v68, v69, v66
	v_mul_f32_e32 v106, 0xbfb8aa3b, v31
	v_fma_f32 v65, -v65, v68, v67
	v_exp_f32_e32 v88, v88
	v_div_fmas_f32 v65, v65, v66, v68
	v_exp_f32_e32 v94, v94
	v_div_scale_f32 v73, vcc, 1.0, v70, 1.0
	v_exp_f32_e32 v100, v100
	v_mul_f32_e32 v74, v73, v72
	v_exp_f32_e32 v106, v106
	v_fma_f32 v75, -v71, v74, v73
	v_add_f32_e32 v88, 1.0, v88
	v_fmac_f32_e32 v74, v75, v72
	v_add_f32_e32 v94, 1.0, v94
	v_fma_f32 v71, -v71, v74, v73
	v_add_f32_e32 v100, 1.0, v100
	v_div_fmas_f32 v71, v71, v72, v74
	v_add_f32_e32 v106, 1.0, v106
	v_div_scale_f32 v79, vcc, 1.0, v76, 1.0
	v_div_scale_f32 v89, s[2:3], v88, v88, 1.0
	v_mul_f32_e32 v80, v79, v78
	v_div_scale_f32 v95, s[2:3], v94, v94, 1.0
	v_fma_f32 v81, -v77, v80, v79
	v_div_scale_f32 v101, s[2:3], v100, v100, 1.0
	v_fmac_f32_e32 v80, v81, v78
	v_div_scale_f32 v107, s[2:3], v106, v106, 1.0
	v_fma_f32 v77, -v77, v80, v79
	v_rcp_f32_e32 v90, v89
	v_div_fmas_f32 v77, v77, v78, v80
	v_rcp_f32_e32 v96, v95
	v_div_scale_f32 v85, vcc, 1.0, v82, 1.0
	v_rcp_f32_e32 v102, v101
	v_mul_f32_e32 v86, v85, v84
	v_rcp_f32_e32 v108, v107
	v_fma_f32 v87, -v83, v86, v85
	v_fma_f32 v93, -v89, v90, 1.0
	v_fmac_f32_e32 v86, v87, v84
	v_fma_f32 v99, -v95, v96, 1.0
	v_fma_f32 v83, -v83, v86, v85
	v_fma_f32 v105, -v101, v102, 1.0
	v_div_fmas_f32 v83, v83, v84, v86
	v_fma_f32 v111, -v107, v108, 1.0
	v_fmac_f32_e32 v90, v93, v90
	v_fmac_f32_e32 v96, v99, v96
	v_fmac_f32_e32 v102, v105, v102
	v_fmac_f32_e32 v108, v111, v108
	v_div_fixup_f32 v65, v65, v64, 1.0
	v_div_fixup_f32 v71, v71, v70, 1.0
	v_div_fixup_f32 v77, v77, v76, 1.0
	v_div_fixup_f32 v83, v83, v82, 1.0
	v_mul_f32_e32 v65, v24, v65
	v_mul_f32_e32 v71, v25, v71
	v_mul_f32_e32 v77, v26, v77
	v_mul_f32_e32 v83, v27, v83
	v_mul_f32_e32 v65, v8, v65
	v_mul_f32_e32 v71, v9, v71
	v_mul_f32_e32 v77, v10, v77
	v_mul_f32_e32 v83, v11, v83
	v_cvt_pk_bf16_f32 v65, v65, v65
	v_cvt_pk_bf16_f32 v71, v71, v71
	v_cvt_pk_bf16_f32 v77, v77, v77
	v_cvt_pk_bf16_f32 v83, v83, v83
	ds_write_b16 v112, v65 offset:1024
	ds_write_b16 v112, v71 offset:1088
	ds_write_b16 v112, v77 offset:1152
	ds_write_b16 v112, v83 offset:1216
	v_div_scale_f32 v91, vcc, 1.0, v88, 1.0
	v_mul_f32_e32 v92, v91, v90
	v_fma_f32 v93, -v89, v92, v91
	v_fmac_f32_e32 v92, v93, v90
	v_fma_f32 v89, -v89, v92, v91
	v_div_fmas_f32 v89, v89, v90, v92
	v_div_scale_f32 v97, vcc, 1.0, v94, 1.0
	v_mul_f32_e32 v98, v97, v96
	v_fma_f32 v99, -v95, v98, v97
	v_fmac_f32_e32 v98, v99, v96
	v_fma_f32 v95, -v95, v98, v97
	v_div_fmas_f32 v95, v95, v96, v98
	v_div_scale_f32 v103, vcc, 1.0, v100, 1.0
	v_mul_f32_e32 v104, v103, v102
	v_fma_f32 v105, -v101, v104, v103
	v_fmac_f32_e32 v104, v105, v102
	v_fma_f32 v101, -v101, v104, v103
	v_div_fmas_f32 v101, v101, v102, v104
	v_div_scale_f32 v109, vcc, 1.0, v106, 1.0
	v_mul_f32_e32 v110, v109, v108
	v_fma_f32 v111, -v107, v110, v109
	v_fmac_f32_e32 v110, v111, v108
	v_fma_f32 v107, -v107, v110, v109
	v_div_fmas_f32 v107, v107, v108, v110
	v_div_fixup_f32 v89, v89, v88, 1.0
	v_div_fixup_f32 v95, v95, v94, 1.0
	v_div_fixup_f32 v101, v101, v100, 1.0
	v_div_fixup_f32 v107, v107, v106, 1.0
	v_mul_f32_e32 v89, v28, v89
	v_mul_f32_e32 v95, v29, v95
	v_mul_f32_e32 v101, v30, v101
	v_mul_f32_e32 v107, v31, v107
	v_mul_f32_e32 v89, v12, v89
	v_mul_f32_e32 v95, v13, v95
	v_mul_f32_e32 v101, v14, v101
	v_mul_f32_e32 v107, v15, v107
	v_cvt_pk_bf16_f32 v89, v89, v89
	v_cvt_pk_bf16_f32 v95, v95, v95
	v_cvt_pk_bf16_f32 v101, v101, v101
	v_cvt_pk_bf16_f32 v107, v107, v107
	ds_write_b16 v112, v89 offset:1536
	ds_write_b16 v112, v95 offset:1600
	ds_write_b16 v112, v101 offset:1664
	ds_write_b16 v112, v107 offset:1728
	ds_read_b128 v[120:123], v113
	ds_read_b128 v[124:127], v113 offset:1024
	s_waitcnt lgkmcnt(0)
	global_store_dwordx4 v114, v[120:123], s[98:99]
	s_add_u32 s98, s98, 0x16000
	s_addc_u32 s99, s99, 0
	global_store_dwordx4 v114, v[124:127], s[98:99]
	s_add_u32 s98, s98, 0x16000
	s_addc_u32 s99, s99, 0
	s_add_i32 s57, s57, s92
	s_cmpk_gt_i32 s57, 0xfff
	s_cbranch_scc1 .LBB0_1043

.LBB0_1043:
	s_cmp_ge_u32 s33, 0x100
	s_cbranch_scc1 .Lffh2_skip
	s_lshr_b32 s57, s33, 1
	s_addk_i32 s57, 0x1000
	s_and_b32 s98, s57, 7
	s_bfe_u32 s99, s57, 0x60003
	s_lshr_b32 s100, s57, 9
	s_lshl_b32 s100, s100, 6
	s_add_u32 s99, s99, s100
	s_mul_hi_u32 s100, s99, 0xaaaaaaab
	s_lshr_b32 s100, s100, 3
	s_mul_i32 s101, s100, 12
	s_sub_u32 s99, s99, s101
	s_mul_i32 s98, s98, 12
	s_add_u32 s98, s98, s99
	s_lshl_b32 s48, s98, 7
	s_lshl_b32 s49, s100, 7
	s_and_b32 s98, s33, 1
	s_lshl_b32 s98, s98, 6
	s_add_u32 s48, s48, s98
	v_lshl_or_b32 v32, v183, 3, v191
	v_and_b32_e32 v33, 63, v32
	v_lshrrev_b32_e32 v34, 3, v33
	v_lshrrev_b32_e32 v35, 4, v33
	v_xor_b32_e32 v35, v35, v33
	v_and_b32_e32 v35, 7, v35
	v_lshlrev_b32_e32 v35, 4, v35
	s_movk_i32 s101, 0x800
	v_mad_u32_u24 v68, v34, s101, v35
	v_xor_b32_e32 v36, 64, v68
	v_add_u32_e32 v69, 0x3c00, v36
	v_add_u32_e32 v70, 0x7800, v68
	v_add_u32_e32 v71, 0xb400, v36
	v_and_b32_e32 v37, 31, v32
	v_bfe_u32 v38, v32, 5, 1
	v_bfe_u32 v39, v32, 1, 3
	v_xor_b32_e32 v39, v39, v38
	v_lshlrev_b32_e32 v39, 4, v39
	v_bfe_u32 v40, v32, 7, 1
	v_lshl_or_b32 v40, v40, 6, v37
	v_lshl_add_u32 v72, v40, 7, v39
	v_bfe_u32 v41, v32, 6, 1
	v_lshl_or_b32 v41, v41, 5, v37
	v_lshl_add_u32 v76, v41, 7, v39
	v_add_u32_e32 v76, 0x4000, v76
	v_xor_b32_e32 v73, 32, v72
	v_xor_b32_e32 v77, 32, v76
	v_xor_b32_e32 v74, 64, v72
	v_xor_b32_e32 v78, 64, v76
	v_xor_b32_e32 v75, 96, v72
	v_xor_b32_e32 v79, 96, v76
	v_lshrrev_b32_e32 v42, 6, v32
	s_nop 0
	v_readfirstlane_b32 s57, v42
	s_nop 3
	s_lshl_b32 s98, s57, 12
	s_lshl_b32 s99, s57, 11
	s_add_u32 s99, s99, 0x4000
	s_lshl_b32 s101, s57, 5
	s_add_u32 s101, s101, s49
	s_mul_i32 s101, s101, 0x800
	s_add_u32 s101, s101, 0xb40000
	s_add_u32 s2, s90, s101
	s_addc_u32 s3, s91, 0
	s_lshl_b32 s101, s57, 4
	s_add_u32 s101, s101, s48
	s_mul_i32 s101, s101, 0x800
	s_add_u32 s101, s101, 0xb171900
	s_add_u32 s6, s90, s101
	s_addc_u32 s7, s91, 0
	s_add_u32 m0, s98, 0x0
	s_nop 0
	global_load_lds_dwordx4 v68, s[2:3] offset:0
	global_load_lds_dwordx4 v69, s[2:3] offset:1024
	global_load_lds_dwordx4 v70, s[2:3] offset:2048
	global_load_lds_dwordx4 v71, s[2:3] offset:3072
	s_add_u32 m0, s99, 0x0
	s_nop 0
	global_load_lds_dwordx4 v68, s[6:7] offset:0
	global_load_lds_dwordx4 v69, s[6:7] offset:1024
	s_add_u32 s2, s2, 0x80
	s_addc_u32 s3, s3, 0
	s_add_u32 s6, s6, 0x80
	s_addc_u32 s7, s7, 0
	s_add_u32 m0, s98, 0x8000
	s_nop 0
	global_load_lds_dwordx4 v68, s[2:3] offset:0
	global_load_lds_dwordx4 v69, s[2:3] offset:1024
	global_load_lds_dwordx4 v70, s[2:3] offset:2048
	global_load_lds_dwordx4 v71, s[2:3] offset:3072
	s_add_u32 m0, s99, 0x8000
	s_nop 0
	global_load_lds_dwordx4 v68, s[6:7] offset:0
	global_load_lds_dwordx4 v69, s[6:7] offset:1024
	s_add_u32 s2, s2, 0x80
	s_addc_u32 s3, s3, 0
	s_add_u32 s6, s6, 0x80
	s_addc_u32 s7, s7, 0
	v_mov_b32_e32 v0, 0
	v_mov_b32_e32 v1, 0
	v_mov_b32_e32 v2, 0
	v_mov_b32_e32 v3, 0
	v_mov_b32_e32 v4, 0
	v_mov_b32_e32 v5, 0
	v_mov_b32_e32 v6, 0
	v_mov_b32_e32 v7, 0
	v_mov_b32_e32 v8, 0
	v_mov_b32_e32 v9, 0
	v_mov_b32_e32 v10, 0
	v_mov_b32_e32 v11, 0
	v_mov_b32_e32 v12, 0
	v_mov_b32_e32 v13, 0
	v_mov_b32_e32 v14, 0
	v_mov_b32_e32 v15, 0
	v_mov_b32_e32 v16, 0
	v_mov_b32_e32 v17, 0
	v_mov_b32_e32 v18, 0
	v_mov_b32_e32 v19, 0
	v_mov_b32_e32 v20, 0
	v_mov_b32_e32 v21, 0
	v_mov_b32_e32 v22, 0
	v_mov_b32_e32 v23, 0
	v_mov_b32_e32 v24, 0
	v_mov_b32_e32 v25, 0
	v_mov_b32_e32 v26, 0
	v_mov_b32_e32 v27, 0
	v_mov_b32_e32 v28, 0
	v_mov_b32_e32 v29, 0
	v_mov_b32_e32 v30, 0
	v_mov_b32_e32 v31, 0
	s_movk_i32 s100, 7
	s_waitcnt vmcnt(6)
.Lgfh2_loop:
	s_waitcnt vmcnt(6)
	s_barrier
	ds_read_b128 v[32:35], v72 offset:0
	ds_read_b128 v[40:43], v76 offset:0
	ds_read_b128 v[36:39], v72 offset:4096
	ds_read_b128 v[44:47], v73 offset:0
	ds_read_b128 v[52:55], v77 offset:0
	ds_read_b128 v[48:51], v73 offset:4096
	s_waitcnt lgkmcnt(3)
	v_mfma_f32_32x32x16_bf16 v[0:15], v[40:43], v[32:35], v[0:15]
	ds_read_b128 v[56:59], v74 offset:0
	ds_read_b128 v[64:67], v78 offset:0
	v_mfma_f32_32x32x16_bf16 v[16:31], v[40:43], v[36:39], v[16:31]
	ds_read_b128 v[60:63], v74 offset:4096
	s_waitcnt lgkmcnt(3)
	v_mfma_f32_32x32x16_bf16 v[0:15], v[52:55], v[44:47], v[0:15]
	ds_read_b128 v[32:35], v75 offset:0
	ds_read_b128 v[40:43], v79 offset:0
	v_mfma_f32_32x32x16_bf16 v[16:31], v[52:55], v[48:51], v[16:31]
	ds_read_b128 v[36:39], v75 offset:4096
	s_waitcnt lgkmcnt(3)
	v_mfma_f32_32x32x16_bf16 v[0:15], v[64:67], v[56:59], v[0:15]
	v_mfma_f32_32x32x16_bf16 v[16:31], v[64:67], v[60:63], v[16:31]
	s_waitcnt lgkmcnt(0)
	v_mfma_f32_32x32x16_bf16 v[0:15], v[40:43], v[32:35], v[0:15]
	v_mfma_f32_32x32x16_bf16 v[16:31], v[40:43], v[36:39], v[16:31]
	s_barrier
	s_add_u32 m0, s98, 0x0
	s_nop 0
	global_load_lds_dwordx4 v68, s[2:3] offset:0
	global_load_lds_dwordx4 v69, s[2:3] offset:1024
	global_load_lds_dwordx4 v70, s[2:3] offset:2048
	global_load_lds_dwordx4 v71, s[2:3] offset:3072
	s_add_u32 m0, s99, 0x0
	s_nop 0
	global_load_lds_dwordx4 v68, s[6:7] offset:0
	global_load_lds_dwordx4 v69, s[6:7] offset:1024
	s_add_u32 s2, s2, 0x80
	s_addc_u32 s3, s3, 0
	s_add_u32 s6, s6, 0x80
	s_addc_u32 s7, s7, 0
	s_waitcnt vmcnt(6)
	s_barrier
	ds_read_b128 v[32:35], v72 offset:32768
	ds_read_b128 v[40:43], v76 offset:32768
	ds_read_b128 v[36:39], v72 offset:36864
	ds_read_b128 v[44:47], v73 offset:32768
	ds_read_b128 v[52:55], v77 offset:32768
	ds_read_b128 v[48:51], v73 offset:36864
	s_waitcnt lgkmcnt(3)
	v_mfma_f32_32x32x16_bf16 v[0:15], v[40:43], v[32:35], v[0:15]
	ds_read_b128 v[56:59], v74 offset:32768
	ds_read_b128 v[64:67], v78 offset:32768
	v_mfma_f32_32x32x16_bf16 v[16:31], v[40:43], v[36:39], v[16:31]
	ds_read_b128 v[60:63], v74 offset:36864
	s_waitcnt lgkmcnt(3)
	v_mfma_f32_32x32x16_bf16 v[0:15], v[52:55], v[44:47], v[0:15]
	ds_read_b128 v[32:35], v75 offset:32768
	ds_read_b128 v[40:43], v79 offset:32768
	v_mfma_f32_32x32x16_bf16 v[16:31], v[52:55], v[48:51], v[16:31]
	ds_read_b128 v[36:39], v75 offset:36864
	s_waitcnt lgkmcnt(3)
	v_mfma_f32_32x32x16_bf16 v[0:15], v[64:67], v[56:59], v[0:15]
	v_mfma_f32_32x32x16_bf16 v[16:31], v[64:67], v[60:63], v[16:31]
	s_waitcnt lgkmcnt(0)
	v_mfma_f32_32x32x16_bf16 v[0:15], v[40:43], v[32:35], v[0:15]
	v_mfma_f32_32x32x16_bf16 v[16:31], v[40:43], v[36:39], v[16:31]
	s_barrier
	s_add_u32 m0, s98, 0x8000
	s_nop 0
	global_load_lds_dwordx4 v68, s[2:3] offset:0
	global_load_lds_dwordx4 v69, s[2:3] offset:1024
	global_load_lds_dwordx4 v70, s[2:3] offset:2048
	global_load_lds_dwordx4 v71, s[2:3] offset:3072
	s_add_u32 m0, s99, 0x8000
	s_nop 0
	global_load_lds_dwordx4 v68, s[6:7] offset:0
	global_load_lds_dwordx4 v69, s[6:7] offset:1024
	s_add_u32 s2, s2, 0x80
	s_addc_u32 s3, s3, 0
	s_add_u32 s6, s6, 0x80
	s_addc_u32 s7, s7, 0
	s_sub_u32 s100, s100, 1
	s_cmp_lg_u32 s100, 0
	s_cbranch_scc1 .Lgfh2_loop
	s_waitcnt vmcnt(6)
	s_barrier
	ds_read_b128 v[32:35], v72 offset:0
	ds_read_b128 v[40:43], v76 offset:0
	ds_read_b128 v[36:39], v72 offset:4096
	ds_read_b128 v[44:47], v73 offset:0
	ds_read_b128 v[52:55], v77 offset:0
	ds_read_b128 v[48:51], v73 offset:4096
	s_waitcnt lgkmcnt(3)
	v_mfma_f32_32x32x16_bf16 v[0:15], v[40:43], v[32:35], v[0:15]
	ds_read_b128 v[56:59], v74 offset:0
	ds_read_b128 v[64:67], v78 offset:0
	v_mfma_f32_32x32x16_bf16 v[16:31], v[40:43], v[36:39], v[16:31]
	ds_read_b128 v[60:63], v74 offset:4096
	s_waitcnt lgkmcnt(3)
	v_mfma_f32_32x32x16_bf16 v[0:15], v[52:55], v[44:47], v[0:15]
	ds_read_b128 v[32:35], v75 offset:0
	ds_read_b128 v[40:43], v79 offset:0
	v_mfma_f32_32x32x16_bf16 v[16:31], v[52:55], v[48:51], v[16:31]
	ds_read_b128 v[36:39], v75 offset:4096
	s_waitcnt lgkmcnt(3)
	v_mfma_f32_32x32x16_bf16 v[0:15], v[64:67], v[56:59], v[0:15]
	v_mfma_f32_32x32x16_bf16 v[16:31], v[64:67], v[60:63], v[16:31]
	s_waitcnt lgkmcnt(0)
	v_mfma_f32_32x32x16_bf16 v[0:15], v[40:43], v[32:35], v[0:15]
	v_mfma_f32_32x32x16_bf16 v[16:31], v[40:43], v[36:39], v[16:31]
	s_barrier
	s_waitcnt vmcnt(0)
	s_barrier
	ds_read_b128 v[32:35], v72 offset:32768
	ds_read_b128 v[40:43], v76 offset:32768
	ds_read_b128 v[36:39], v72 offset:36864
	ds_read_b128 v[44:47], v73 offset:32768
	ds_read_b128 v[52:55], v77 offset:32768
	ds_read_b128 v[48:51], v73 offset:36864
	s_waitcnt lgkmcnt(3)
	v_mfma_f32_32x32x16_bf16 v[0:15], v[40:43], v[32:35], v[0:15]
	ds_read_b128 v[56:59], v74 offset:32768
	ds_read_b128 v[64:67], v78 offset:32768
	v_mfma_f32_32x32x16_bf16 v[16:31], v[40:43], v[36:39], v[16:31]
	ds_read_b128 v[60:63], v74 offset:36864
	s_waitcnt lgkmcnt(3)
	v_mfma_f32_32x32x16_bf16 v[0:15], v[52:55], v[44:47], v[0:15]
	ds_read_b128 v[32:35], v75 offset:32768
	ds_read_b128 v[40:43], v79 offset:32768
	v_mfma_f32_32x32x16_bf16 v[16:31], v[52:55], v[48:51], v[16:31]
	ds_read_b128 v[36:39], v75 offset:36864
	s_waitcnt lgkmcnt(3)
	v_mfma_f32_32x32x16_bf16 v[0:15], v[64:67], v[56:59], v[0:15]
	v_mfma_f32_32x32x16_bf16 v[16:31], v[64:67], v[60:63], v[16:31]
	s_waitcnt lgkmcnt(0)
	v_mfma_f32_32x32x16_bf16 v[0:15], v[40:43], v[32:35], v[0:15]
	v_mfma_f32_32x32x16_bf16 v[16:31], v[40:43], v[36:39], v[16:31]
	s_barrier
	s_nop 7
	s_nop 7
	s_branch .Lffh2_epi
.Lffh2_epi:
	v_lshl_or_b32 v115, v183, 3, v191
	v_lshrrev_b32_e32 v116, 6, v115
	v_and_b32_e32 v117, 63, v115
	v_lshlrev_b32_e32 v113, 11, v116
	v_add_u32_e32 v113, 0x10000, v113
	v_readfirstlane_b32 s100, v116
	v_and_b32_e32 v112, 31, v117
	v_lshl_add_u32 v112, v112, 1, v113
	v_lshrrev_b32_e32 v116, 5, v117
	v_lshl_add_u32 v112, v116, 8, v112
	v_lshl_add_u32 v113, v117, 4, v113
	v_lshrrev_b32_e32 v116, 2, v117
	v_mul_u32_u24_e32 v116, 0x1600, v116
	v_and_b32_e32 v114, 3, v117
	v_lshl_add_u32 v114, v114, 4, v116
	s_and_b32 s101, s100, 1
	s_lshl_b32 s101, s101, 5
	s_add_u32 s101, s101, s48
	s_mul_i32 s101, s101, 0x1600
	s_lshr_b32 s100, s100, 1
	s_lshl_b32 s100, s100, 6
	s_add_u32 s100, s100, s49
	s_add_u32 s101, s101, s100
	s_add_u32 s98, s90, 0x3971900
	s_addc_u32 s99, s91, 0
	s_add_u32 s98, s98, s101
	s_addc_u32 s99, s99, 0
	v_mul_f32_e32 v64, 0xbfb8aa3b, v0
	v_mul_f32_e32 v70, 0xbfb8aa3b, v1
	v_mul_f32_e32 v76, 0xbfb8aa3b, v2
	v_mul_f32_e32 v82, 0xbfb8aa3b, v3
	v_exp_f32_e32 v64, v64
	v_exp_f32_e32 v70, v70
	v_exp_f32_e32 v76, v76
	v_exp_f32_e32 v82, v82
	v_add_f32_e32 v64, 1.0, v64
	v_add_f32_e32 v70, 1.0, v70
	v_add_f32_e32 v76, 1.0, v76
	v_add_f32_e32 v82, 1.0, v82
	v_div_scale_f32 v65, s[2:3], v64, v64, 1.0
	v_div_scale_f32 v71, s[2:3], v70, v70, 1.0
	v_div_scale_f32 v77, s[2:3], v76, v76, 1.0
	v_div_scale_f32 v83, s[2:3], v82, v82, 1.0
	v_rcp_f32_e32 v66, v65
	v_rcp_f32_e32 v72, v71
	v_rcp_f32_e32 v78, v77
	v_rcp_f32_e32 v84, v83
	v_fma_f32 v69, -v65, v66, 1.0
	v_fma_f32 v75, -v71, v72, 1.0
	v_fma_f32 v81, -v77, v78, 1.0
	v_fma_f32 v87, -v83, v84, 1.0
	v_fmac_f32_e32 v66, v69, v66
	v_fmac_f32_e32 v72, v75, v72
	v_fmac_f32_e32 v78, v81, v78
	v_fmac_f32_e32 v84, v87, v84
	v_div_scale_f32 v67, vcc, 1.0, v64, 1.0
	v_mul_f32_e32 v88, 0xbfb8aa3b, v4
	v_mul_f32_e32 v68, v67, v66
	v_mul_f32_e32 v94, 0xbfb8aa3b, v5
	v_fma_f32 v69, -v65, v68, v67
	v_mul_f32_e32 v100, 0xbfb8aa3b, v6
	v_fmac_f32_e32 v68, v69, v66
	v_mul_f32_e32 v106, 0xbfb8aa3b, v7
	v_fma_f32 v65, -v65, v68, v67
	v_exp_f32_e32 v88, v88
	v_div_fmas_f32 v65, v65, v66, v68
	v_exp_f32_e32 v94, v94
	v_div_scale_f32 v73, vcc, 1.0, v70, 1.0
	v_exp_f32_e32 v100, v100
	v_mul_f32_e32 v74, v73, v72
	v_exp_f32_e32 v106, v106
	v_fma_f32 v75, -v71, v74, v73
	v_add_f32_e32 v88, 1.0, v88
	v_fmac_f32_e32 v74, v75, v72
	v_add_f32_e32 v94, 1.0, v94
	v_fma_f32 v71, -v71, v74, v73
	v_add_f32_e32 v100, 1.0, v100
	v_div_fmas_f32 v71, v71, v72, v74
	v_add_f32_e32 v106, 1.0, v106
	v_div_scale_f32 v79, vcc, 1.0, v76, 1.0
	v_div_scale_f32 v89, s[2:3], v88, v88, 1.0
	v_mul_f32_e32 v80, v79, v78
	v_div_scale_f32 v95, s[2:3], v94, v94, 1.0
	v_fma_f32 v81, -v77, v80, v79
	v_div_scale_f32 v101, s[2:3], v100, v100, 1.0
	v_fmac_f32_e32 v80, v81, v78
	v_div_scale_f32 v107, s[2:3], v106, v106, 1.0
	v_fma_f32 v77, -v77, v80, v79
	v_rcp_f32_e32 v90, v89
	v_div_fmas_f32 v77, v77, v78, v80
	v_rcp_f32_e32 v96, v95
	v_div_scale_f32 v85, vcc, 1.0, v82, 1.0
	v_rcp_f32_e32 v102, v101
	v_mul_f32_e32 v86, v85, v84
	v_rcp_f32_e32 v108, v107
	v_fma_f32 v87, -v83, v86, v85
	v_fma_f32 v93, -v89, v90, 1.0
	v_fmac_f32_e32 v86, v87, v84
	v_fma_f32 v99, -v95, v96, 1.0
	v_fma_f32 v83, -v83, v86, v85
	v_fma_f32 v105, -v101, v102, 1.0
	v_div_fmas_f32 v83, v83, v84, v86
	v_fma_f32 v111, -v107, v108, 1.0
	v_fmac_f32_e32 v90, v93, v90
	v_fmac_f32_e32 v96, v99, v96
	v_fmac_f32_e32 v102, v105, v102
	v_fmac_f32_e32 v108, v111, v108
	v_div_fixup_f32 v65, v65, v64, 1.0
	v_div_fixup_f32 v71, v71, v70, 1.0
	v_div_fixup_f32 v77, v77, v76, 1.0
	v_div_fixup_f32 v83, v83, v82, 1.0
	v_mul_f32_e32 v65, v0, v65
	v_mul_f32_e32 v71, v1, v71
	v_mul_f32_e32 v77, v2, v77
	v_mul_f32_e32 v83, v3, v83
	v_mul_f32_e32 v65, v16, v65
	v_mul_f32_e32 v71, v17, v71
	v_mul_f32_e32 v77, v18, v77
	v_mul_f32_e32 v83, v19, v83
	v_cvt_pk_bf16_f32 v65, v65, v65
	v_cvt_pk_bf16_f32 v71, v71, v71
	v_cvt_pk_bf16_f32 v77, v77, v77
	v_cvt_pk_bf16_f32 v83, v83, v83
	ds_write_b16 v112, v65
	ds_write_b16 v112, v71 offset:64
	ds_write_b16 v112, v77 offset:128
	ds_write_b16 v112, v83 offset:192
	v_div_scale_f32 v91, vcc, 1.0, v88, 1.0
	v_mul_f32_e32 v64, 0xbfb8aa3b, v8
	v_mul_f32_e32 v92, v91, v90
	v_mul_f32_e32 v70, 0xbfb8aa3b, v9
	v_fma_f32 v93, -v89, v92, v91
	v_mul_f32_e32 v76, 0xbfb8aa3b, v10
	v_fmac_f32_e32 v92, v93, v90
	v_mul_f32_e32 v82, 0xbfb8aa3b, v11
	v_fma_f32 v89, -v89, v92, v91
	v_exp_f32_e32 v64, v64
	v_div_fmas_f32 v89, v89, v90, v92
	v_exp_f32_e32 v70, v70
	v_div_scale_f32 v97, vcc, 1.0, v94, 1.0
	v_exp_f32_e32 v76, v76
	v_mul_f32_e32 v98, v97, v96
	v_exp_f32_e32 v82, v82
	v_fma_f32 v99, -v95, v98, v97
	v_add_f32_e32 v64, 1.0, v64
	v_fmac_f32_e32 v98, v99, v96
	v_add_f32_e32 v70, 1.0, v70
	v_fma_f32 v95, -v95, v98, v97
	v_add_f32_e32 v76, 1.0, v76
	v_div_fmas_f32 v95, v95, v96, v98
	v_add_f32_e32 v82, 1.0, v82
	v_div_scale_f32 v103, vcc, 1.0, v100, 1.0
	v_div_scale_f32 v65, s[2:3], v64, v64, 1.0
	v_mul_f32_e32 v104, v103, v102
	v_div_scale_f32 v71, s[2:3], v70, v70, 1.0
	v_fma_f32 v105, -v101, v104, v103
	v_div_scale_f32 v77, s[2:3], v76, v76, 1.0
	v_fmac_f32_e32 v104, v105, v102
	v_div_scale_f32 v83, s[2:3], v82, v82, 1.0
	v_fma_f32 v101, -v101, v104, v103
	v_rcp_f32_e32 v66, v65
	v_div_fmas_f32 v101, v101, v102, v104
	v_rcp_f32_e32 v72, v71
	v_div_scale_f32 v109, vcc, 1.0, v106, 1.0
	v_rcp_f32_e32 v78, v77
	v_mul_f32_e32 v110, v109, v108
	v_rcp_f32_e32 v84, v83
	v_fma_f32 v111, -v107, v110, v109
	v_fma_f32 v69, -v65, v66, 1.0
	v_fmac_f32_e32 v110, v111, v108
	v_fma_f32 v75, -v71, v72, 1.0
	v_fma_f32 v107, -v107, v110, v109
	v_fma_f32 v81, -v77, v78, 1.0
	v_div_fmas_f32 v107, v107, v108, v110
	v_fma_f32 v87, -v83, v84, 1.0
	v_fmac_f32_e32 v66, v69, v66
	v_fmac_f32_e32 v72, v75, v72
	v_fmac_f32_e32 v78, v81, v78
	v_fmac_f32_e32 v84, v87, v84
	v_div_fixup_f32 v89, v89, v88, 1.0
	v_div_fixup_f32 v95, v95, v94, 1.0
	v_div_fixup_f32 v101, v101, v100, 1.0
	v_div_fixup_f32 v107, v107, v106, 1.0
	v_mul_f32_e32 v89, v4, v89
	v_mul_f32_e32 v95, v5, v95
	v_mul_f32_e32 v101, v6, v101
	v_mul_f32_e32 v107, v7, v107
	v_mul_f32_e32 v89, v20, v89
	v_mul_f32_e32 v95, v21, v95
	v_mul_f32_e32 v101, v22, v101
	v_mul_f32_e32 v107, v23, v107
	v_cvt_pk_bf16_f32 v89, v89, v89
	v_cvt_pk_bf16_f32 v95, v95, v95
	v_cvt_pk_bf16_f32 v101, v101, v101
	v_cvt_pk_bf16_f32 v107, v107, v107
	ds_write_b16 v112, v89 offset:512
	ds_write_b16 v112, v95 offset:576
	ds_write_b16 v112, v101 offset:640
	ds_write_b16 v112, v107 offset:704
	v_div_scale_f32 v67, vcc, 1.0, v64, 1.0
	v_mul_f32_e32 v88, 0xbfb8aa3b, v12
	v_mul_f32_e32 v68, v67, v66
	v_mul_f32_e32 v94, 0xbfb8aa3b, v13
	v_fma_f32 v69, -v65, v68, v67
	v_mul_f32_e32 v100, 0xbfb8aa3b, v14
	v_fmac_f32_e32 v68, v69, v66
	v_mul_f32_e32 v106, 0xbfb8aa3b, v15
	v_fma_f32 v65, -v65, v68, v67
	v_exp_f32_e32 v88, v88
	v_div_fmas_f32 v65, v65, v66, v68
	v_exp_f32_e32 v94, v94
	v_div_scale_f32 v73, vcc, 1.0, v70, 1.0
	v_exp_f32_e32 v100, v100
	v_mul_f32_e32 v74, v73, v72
	v_exp_f32_e32 v106, v106
	v_fma_f32 v75, -v71, v74, v73
	v_add_f32_e32 v88, 1.0, v88
	v_fmac_f32_e32 v74, v75, v72
	v_add_f32_e32 v94, 1.0, v94
	v_fma_f32 v71, -v71, v74, v73
	v_add_f32_e32 v100, 1.0, v100
	v_div_fmas_f32 v71, v71, v72, v74
	v_add_f32_e32 v106, 1.0, v106
	v_div_scale_f32 v79, vcc, 1.0, v76, 1.0
	v_div_scale_f32 v89, s[2:3], v88, v88, 1.0
	v_mul_f32_e32 v80, v79, v78
	v_div_scale_f32 v95, s[2:3], v94, v94, 1.0
	v_fma_f32 v81, -v77, v80, v79
	v_div_scale_f32 v101, s[2:3], v100, v100, 1.0
	v_fmac_f32_e32 v80, v81, v78
	v_div_scale_f32 v107, s[2:3], v106, v106, 1.0
	v_fma_f32 v77, -v77, v80, v79
	v_rcp_f32_e32 v90, v89
	v_div_fmas_f32 v77, v77, v78, v80
	v_rcp_f32_e32 v96, v95
	v_div_scale_f32 v85, vcc, 1.0, v82, 1.0
	v_rcp_f32_e32 v102, v101
	v_mul_f32_e32 v86, v85, v84
	v_rcp_f32_e32 v108, v107
	v_fma_f32 v87, -v83, v86, v85
	v_fma_f32 v93, -v89, v90, 1.0
	v_fmac_f32_e32 v86, v87, v84
	v_fma_f32 v99, -v95, v96, 1.0
	v_fma_f32 v83, -v83, v86, v85
	v_fma_f32 v105, -v101, v102, 1.0
	v_div_fmas_f32 v83, v83, v84, v86
	v_fma_f32 v111, -v107, v108, 1.0
	v_fmac_f32_e32 v90, v93, v90
	v_fmac_f32_e32 v96, v99, v96
	v_fmac_f32_e32 v102, v105, v102
	v_fmac_f32_e32 v108, v111, v108
	v_div_fixup_f32 v65, v65, v64, 1.0
	v_div_fixup_f32 v71, v71, v70, 1.0
	v_div_fixup_f32 v77, v77, v76, 1.0
	v_div_fixup_f32 v83, v83, v82, 1.0
	v_mul_f32_e32 v65, v8, v65
	v_mul_f32_e32 v71, v9, v71
	v_mul_f32_e32 v77, v10, v77
	v_mul_f32_e32 v83, v11, v83
	v_mul_f32_e32 v65, v24, v65
	v_mul_f32_e32 v71, v25, v71
	v_mul_f32_e32 v77, v26, v77
	v_mul_f32_e32 v83, v27, v83
	v_cvt_pk_bf16_f32 v65, v65, v65
	v_cvt_pk_bf16_f32 v71, v71, v71
	v_cvt_pk_bf16_f32 v77, v77, v77
	v_cvt_pk_bf16_f32 v83, v83, v83
	ds_write_b16 v112, v65 offset:1024
	ds_write_b16 v112, v71 offset:1088
	ds_write_b16 v112, v77 offset:1152
	ds_write_b16 v112, v83 offset:1216
	v_div_scale_f32 v91, vcc, 1.0, v88, 1.0
	v_mul_f32_e32 v92, v91, v90
	v_fma_f32 v93, -v89, v92, v91
	v_fmac_f32_e32 v92, v93, v90
	v_fma_f32 v89, -v89, v92, v91
	v_div_fmas_f32 v89, v89, v90, v92
	v_div_scale_f32 v97, vcc, 1.0, v94, 1.0
	v_mul_f32_e32 v98, v97, v96
	v_fma_f32 v99, -v95, v98, v97
	v_fmac_f32_e32 v98, v99, v96
	v_fma_f32 v95, -v95, v98, v97
	v_div_fmas_f32 v95, v95, v96, v98
	v_div_scale_f32 v103, vcc, 1.0, v100, 1.0
	v_mul_f32_e32 v104, v103, v102
	v_fma_f32 v105, -v101, v104, v103
	v_fmac_f32_e32 v104, v105, v102
	v_fma_f32 v101, -v101, v104, v103
	v_div_fmas_f32 v101, v101, v102, v104
	v_div_scale_f32 v109, vcc, 1.0, v106, 1.0
	v_mul_f32_e32 v110, v109, v108
	v_fma_f32 v111, -v107, v110, v109
	v_fmac_f32_e32 v110, v111, v108
	v_fma_f32 v107, -v107, v110, v109
	v_div_fmas_f32 v107, v107, v108, v110
	v_div_fixup_f32 v89, v89, v88, 1.0
	v_div_fixup_f32 v95, v95, v94, 1.0
	v_div_fixup_f32 v101, v101, v100, 1.0
	v_div_fixup_f32 v107, v107, v106, 1.0
	v_mul_f32_e32 v89, v12, v89
	v_mul_f32_e32 v95, v13, v95
	v_mul_f32_e32 v101, v14, v101
	v_mul_f32_e32 v107, v15, v107
	v_mul_f32_e32 v89, v28, v89
	v_mul_f32_e32 v95, v29, v95
	v_mul_f32_e32 v101, v30, v101
	v_mul_f32_e32 v107, v31, v107
	v_cvt_pk_bf16_f32 v89, v89, v89
	v_cvt_pk_bf16_f32 v95, v95, v95
	v_cvt_pk_bf16_f32 v101, v101, v101
	v_cvt_pk_bf16_f32 v107, v107, v107
	ds_write_b16 v112, v89 offset:1536
	ds_write_b16 v112, v95 offset:1600
	ds_write_b16 v112, v101 offset:1664
	ds_write_b16 v112, v107 offset:1728
	ds_read_b128 v[120:123], v113
	ds_read_b128 v[124:127], v113 offset:1024
	s_waitcnt lgkmcnt(0)
	global_store_dwordx4 v114, v[120:123], s[98:99]
	s_add_u32 s98, s98, 0x16000
	s_addc_u32 s99, s99, 0
	global_store_dwordx4 v114, v[124:127], s[98:99]
	s_add_u32 s98, s98, 0x16000
	s_addc_u32 s99, s99, 0

.LBB0_2283:
	v_lshl_or_b32 v115, v183, 3, v191
	v_lshrrev_b32_e32 v116, 6, v115
	v_and_b32_e32 v117, 63, v115
	v_lshlrev_b32_e32 v113, 11, v116
	v_add_u32_e32 v113, 0x10000, v113
	v_readfirstlane_b32 s100, v116
	v_and_b32_e32 v112, 31, v117
	v_lshl_add_u32 v112, v112, 1, v113
	v_lshrrev_b32_e32 v116, 5, v117
	v_lshl_add_u32 v112, v116, 8, v112
	v_lshl_add_u32 v113, v117, 4, v113
	v_lshrrev_b32_e32 v116, 2, v117
	v_mul_u32_u24_e32 v116, 0x1600, v116
	v_and_b32_e32 v114, 3, v117
	v_lshl_add_u32 v114, v114, 4, v116
	s_lshr_b32 s101, s100, 1
	s_lshl_b32 s101, s101, 6
	s_add_u32 s101, s101, s48
	s_mul_i32 s101, s101, 0x1600
	s_and_b32 s100, s100, 1
	s_lshl_b32 s100, s100, 6
	s_add_u32 s100, s100, s49
	s_add_u32 s101, s101, s100
	s_add_u32 s98, s90, 0x3971900
	s_addc_u32 s99, s91, 0
	s_add_u32 s98, s98, s101
	s_addc_u32 s99, s99, 0
	v_mul_f32_e32 v64, 0xbfb8aa3b, v48
	v_mul_f32_e32 v70, 0xbfb8aa3b, v49
	v_mul_f32_e32 v76, 0xbfb8aa3b, v50
	v_mul_f32_e32 v82, 0xbfb8aa3b, v51
	v_exp_f32_e32 v64, v64
	v_exp_f32_e32 v70, v70
	v_exp_f32_e32 v76, v76
	v_exp_f32_e32 v82, v82
	v_add_f32_e32 v64, 1.0, v64
	v_add_f32_e32 v70, 1.0, v70
	v_add_f32_e32 v76, 1.0, v76
	v_add_f32_e32 v82, 1.0, v82
	v_div_scale_f32 v65, s[4:5], v64, v64, 1.0
	v_div_scale_f32 v71, s[4:5], v70, v70, 1.0
	v_div_scale_f32 v77, s[4:5], v76, v76, 1.0
	v_div_scale_f32 v83, s[4:5], v82, v82, 1.0
	v_rcp_f32_e32 v66, v65
	v_rcp_f32_e32 v72, v71
	v_rcp_f32_e32 v78, v77
	v_rcp_f32_e32 v84, v83
	v_fma_f32 v69, -v65, v66, 1.0
	v_fma_f32 v75, -v71, v72, 1.0
	v_fma_f32 v81, -v77, v78, 1.0
	v_fma_f32 v87, -v83, v84, 1.0
	v_fmac_f32_e32 v66, v69, v66
	v_fmac_f32_e32 v72, v75, v72
	v_fmac_f32_e32 v78, v81, v78
	v_fmac_f32_e32 v84, v87, v84
	v_div_scale_f32 v67, vcc, 1.0, v64, 1.0
	v_mul_f32_e32 v88, 0xbfb8aa3b, v52
	v_mul_f32_e32 v68, v67, v66
	v_mul_f32_e32 v94, 0xbfb8aa3b, v53
	v_fma_f32 v69, -v65, v68, v67
	v_mul_f32_e32 v100, 0xbfb8aa3b, v54
	v_fmac_f32_e32 v68, v69, v66
	v_mul_f32_e32 v106, 0xbfb8aa3b, v55
	v_fma_f32 v65, -v65, v68, v67
	v_exp_f32_e32 v88, v88
	v_div_fmas_f32 v65, v65, v66, v68
	v_exp_f32_e32 v94, v94
	v_div_scale_f32 v73, vcc, 1.0, v70, 1.0
	v_exp_f32_e32 v100, v100
	v_mul_f32_e32 v74, v73, v72
	v_exp_f32_e32 v106, v106
	v_fma_f32 v75, -v71, v74, v73
	v_add_f32_e32 v88, 1.0, v88
	v_fmac_f32_e32 v74, v75, v72
	v_add_f32_e32 v94, 1.0, v94
	v_fma_f32 v71, -v71, v74, v73
	v_add_f32_e32 v100, 1.0, v100
	v_div_fmas_f32 v71, v71, v72, v74
	v_add_f32_e32 v106, 1.0, v106
	v_div_scale_f32 v79, vcc, 1.0, v76, 1.0
	v_div_scale_f32 v89, s[4:5], v88, v88, 1.0
	v_mul_f32_e32 v80, v79, v78
	v_div_scale_f32 v95, s[4:5], v94, v94, 1.0
	v_fma_f32 v81, -v77, v80, v79
	v_div_scale_f32 v101, s[4:5], v100, v100, 1.0
	v_fmac_f32_e32 v80, v81, v78
	v_div_scale_f32 v107, s[4:5], v106, v106, 1.0
	v_fma_f32 v77, -v77, v80, v79
	v_rcp_f32_e32 v90, v89
	v_div_fmas_f32 v77, v77, v78, v80
	v_rcp_f32_e32 v96, v95
	v_div_scale_f32 v85, vcc, 1.0, v82, 1.0
	v_rcp_f32_e32 v102, v101
	v_mul_f32_e32 v86, v85, v84
	v_rcp_f32_e32 v108, v107
	v_fma_f32 v87, -v83, v86, v85
	v_fma_f32 v93, -v89, v90, 1.0
	v_fmac_f32_e32 v86, v87, v84
	v_fma_f32 v99, -v95, v96, 1.0
	v_fma_f32 v83, -v83, v86, v85
	v_fma_f32 v105, -v101, v102, 1.0
	v_div_fmas_f32 v83, v83, v84, v86
	v_fma_f32 v111, -v107, v108, 1.0
	v_fmac_f32_e32 v90, v93, v90
	v_fmac_f32_e32 v96, v99, v96
	v_fmac_f32_e32 v102, v105, v102
	v_fmac_f32_e32 v108, v111, v108
	v_div_fixup_f32 v65, v65, v64, 1.0
	v_div_fixup_f32 v71, v71, v70, 1.0
	v_div_fixup_f32 v77, v77, v76, 1.0
	v_div_fixup_f32 v83, v83, v82, 1.0
	v_mul_f32_e32 v65, v48, v65
	v_mul_f32_e32 v71, v49, v71
	v_mul_f32_e32 v77, v50, v77
	v_mul_f32_e32 v83, v51, v83
	v_mul_f32_e32 v65, v32, v65
	v_mul_f32_e32 v71, v33, v71
	v_mul_f32_e32 v77, v34, v77
	v_mul_f32_e32 v83, v35, v83
	v_cvt_pk_bf16_f32 v65, v65, v65
	v_cvt_pk_bf16_f32 v71, v71, v71
	v_cvt_pk_bf16_f32 v77, v77, v77
	v_cvt_pk_bf16_f32 v83, v83, v83
	ds_write_b16 v112, v65
	ds_write_b16 v112, v71 offset:64
	ds_write_b16 v112, v77 offset:128
	ds_write_b16 v112, v83 offset:192
	v_div_scale_f32 v91, vcc, 1.0, v88, 1.0
	v_mul_f32_e32 v64, 0xbfb8aa3b, v56
	v_mul_f32_e32 v92, v91, v90
	v_mul_f32_e32 v70, 0xbfb8aa3b, v57
	v_fma_f32 v93, -v89, v92, v91
	v_mul_f32_e32 v76, 0xbfb8aa3b, v58
	v_fmac_f32_e32 v92, v93, v90
	v_mul_f32_e32 v82, 0xbfb8aa3b, v59
	v_fma_f32 v89, -v89, v92, v91
	v_exp_f32_e32 v64, v64
	v_div_fmas_f32 v89, v89, v90, v92
	v_exp_f32_e32 v70, v70
	v_div_scale_f32 v97, vcc, 1.0, v94, 1.0
	v_exp_f32_e32 v76, v76
	v_mul_f32_e32 v98, v97, v96
	v_exp_f32_e32 v82, v82
	v_fma_f32 v99, -v95, v98, v97
	v_add_f32_e32 v64, 1.0, v64
	v_fmac_f32_e32 v98, v99, v96
	v_add_f32_e32 v70, 1.0, v70
	v_fma_f32 v95, -v95, v98, v97
	v_add_f32_e32 v76, 1.0, v76
	v_div_fmas_f32 v95, v95, v96, v98
	v_add_f32_e32 v82, 1.0, v82
	v_div_scale_f32 v103, vcc, 1.0, v100, 1.0
	v_div_scale_f32 v65, s[4:5], v64, v64, 1.0
	v_mul_f32_e32 v104, v103, v102
	v_div_scale_f32 v71, s[4:5], v70, v70, 1.0
	v_fma_f32 v105, -v101, v104, v103
	v_div_scale_f32 v77, s[4:5], v76, v76, 1.0
	v_fmac_f32_e32 v104, v105, v102
	v_div_scale_f32 v83, s[4:5], v82, v82, 1.0
	v_fma_f32 v101, -v101, v104, v103
	v_rcp_f32_e32 v66, v65
	v_div_fmas_f32 v101, v101, v102, v104
	v_rcp_f32_e32 v72, v71
	v_div_scale_f32 v109, vcc, 1.0, v106, 1.0
	v_rcp_f32_e32 v78, v77
	v_mul_f32_e32 v110, v109, v108
	v_rcp_f32_e32 v84, v83
	v_fma_f32 v111, -v107, v110, v109
	v_fma_f32 v69, -v65, v66, 1.0
	v_fmac_f32_e32 v110, v111, v108
	v_fma_f32 v75, -v71, v72, 1.0
	v_fma_f32 v107, -v107, v110, v109
	v_fma_f32 v81, -v77, v78, 1.0
	v_div_fmas_f32 v107, v107, v108, v110
	v_fma_f32 v87, -v83, v84, 1.0
	v_fmac_f32_e32 v66, v69, v66
	v_fmac_f32_e32 v72, v75, v72
	v_fmac_f32_e32 v78, v81, v78
	v_fmac_f32_e32 v84, v87, v84
	v_div_fixup_f32 v89, v89, v88, 1.0
	v_div_fixup_f32 v95, v95, v94, 1.0
	v_div_fixup_f32 v101, v101, v100, 1.0
	v_div_fixup_f32 v107, v107, v106, 1.0
	v_mul_f32_e32 v89, v52, v89
	v_mul_f32_e32 v95, v53, v95
	v_mul_f32_e32 v101, v54, v101
	v_mul_f32_e32 v107, v55, v107
	v_mul_f32_e32 v89, v36, v89
	v_mul_f32_e32 v95, v37, v95
	v_mul_f32_e32 v101, v38, v101
	v_mul_f32_e32 v107, v39, v107
	v_cvt_pk_bf16_f32 v89, v89, v89
	v_cvt_pk_bf16_f32 v95, v95, v95
	v_cvt_pk_bf16_f32 v101, v101, v101
	v_cvt_pk_bf16_f32 v107, v107, v107
	ds_write_b16 v112, v89 offset:512
	ds_write_b16 v112, v95 offset:576
	ds_write_b16 v112, v101 offset:640
	ds_write_b16 v112, v107 offset:704
	v_div_scale_f32 v67, vcc, 1.0, v64, 1.0
	v_mul_f32_e32 v88, 0xbfb8aa3b, v60
	v_mul_f32_e32 v68, v67, v66
	v_mul_f32_e32 v94, 0xbfb8aa3b, v61
	v_fma_f32 v69, -v65, v68, v67
	v_mul_f32_e32 v100, 0xbfb8aa3b, v62
	v_fmac_f32_e32 v68, v69, v66
	v_mul_f32_e32 v106, 0xbfb8aa3b, v63
	v_fma_f32 v65, -v65, v68, v67
	v_exp_f32_e32 v88, v88
	v_div_fmas_f32 v65, v65, v66, v68
	v_exp_f32_e32 v94, v94
	v_div_scale_f32 v73, vcc, 1.0, v70, 1.0
	v_exp_f32_e32 v100, v100
	v_mul_f32_e32 v74, v73, v72
	v_exp_f32_e32 v106, v106
	v_fma_f32 v75, -v71, v74, v73
	v_add_f32_e32 v88, 1.0, v88
	v_fmac_f32_e32 v74, v75, v72
	v_add_f32_e32 v94, 1.0, v94
	v_fma_f32 v71, -v71, v74, v73
	v_add_f32_e32 v100, 1.0, v100
	v_div_fmas_f32 v71, v71, v72, v74
	v_add_f32_e32 v106, 1.0, v106
	v_div_scale_f32 v79, vcc, 1.0, v76, 1.0
	v_div_scale_f32 v89, s[4:5], v88, v88, 1.0
	v_mul_f32_e32 v80, v79, v78
	v_div_scale_f32 v95, s[4:5], v94, v94, 1.0
	v_fma_f32 v81, -v77, v80, v79
	v_div_scale_f32 v101, s[4:5], v100, v100, 1.0
	v_fmac_f32_e32 v80, v81, v78
	v_div_scale_f32 v107, s[4:5], v106, v106, 1.0
	v_fma_f32 v77, -v77, v80, v79
	v_rcp_f32_e32 v90, v89
	v_div_fmas_f32 v77, v77, v78, v80
	v_rcp_f32_e32 v96, v95
	v_div_scale_f32 v85, vcc, 1.0, v82, 1.0
	v_rcp_f32_e32 v102, v101
	v_mul_f32_e32 v86, v85, v84
	v_rcp_f32_e32 v108, v107
	v_fma_f32 v87, -v83, v86, v85
	v_fma_f32 v93, -v89, v90, 1.0
	v_fmac_f32_e32 v86, v87, v84
	v_fma_f32 v99, -v95, v96, 1.0
	v_fma_f32 v83, -v83, v86, v85
	v_fma_f32 v105, -v101, v102, 1.0
	v_div_fmas_f32 v83, v83, v84, v86
	v_fma_f32 v111, -v107, v108, 1.0
	v_fmac_f32_e32 v90, v93, v90
	v_fmac_f32_e32 v96, v99, v96
	v_fmac_f32_e32 v102, v105, v102
	v_fmac_f32_e32 v108, v111, v108
	v_div_fixup_f32 v65, v65, v64, 1.0
	v_div_fixup_f32 v71, v71, v70, 1.0
	v_div_fixup_f32 v77, v77, v76, 1.0
	v_div_fixup_f32 v83, v83, v82, 1.0
	v_mul_f32_e32 v65, v56, v65
	v_mul_f32_e32 v71, v57, v71
	v_mul_f32_e32 v77, v58, v77
	v_mul_f32_e32 v83, v59, v83
	v_mul_f32_e32 v65, v40, v65
	v_mul_f32_e32 v71, v41, v71
	v_mul_f32_e32 v77, v42, v77
	v_mul_f32_e32 v83, v43, v83
	v_cvt_pk_bf16_f32 v65, v65, v65
	v_cvt_pk_bf16_f32 v71, v71, v71
	v_cvt_pk_bf16_f32 v77, v77, v77
	v_cvt_pk_bf16_f32 v83, v83, v83
	ds_write_b16 v112, v65 offset:1024
	ds_write_b16 v112, v71 offset:1088
	ds_write_b16 v112, v77 offset:1152
	ds_write_b16 v112, v83 offset:1216
	v_div_scale_f32 v91, vcc, 1.0, v88, 1.0
	v_mul_f32_e32 v64, 0xbfb8aa3b, v16
	v_mul_f32_e32 v92, v91, v90
	v_mul_f32_e32 v70, 0xbfb8aa3b, v17
	v_fma_f32 v93, -v89, v92, v91
	v_mul_f32_e32 v76, 0xbfb8aa3b, v18
	v_fmac_f32_e32 v92, v93, v90
	v_mul_f32_e32 v82, 0xbfb8aa3b, v19
	v_fma_f32 v89, -v89, v92, v91
	v_exp_f32_e32 v64, v64
	v_div_fmas_f32 v89, v89, v90, v92
	v_exp_f32_e32 v70, v70
	v_div_scale_f32 v97, vcc, 1.0, v94, 1.0
	v_exp_f32_e32 v76, v76
	v_mul_f32_e32 v98, v97, v96
	v_exp_f32_e32 v82, v82
	v_fma_f32 v99, -v95, v98, v97
	v_add_f32_e32 v64, 1.0, v64
	v_fmac_f32_e32 v98, v99, v96
	v_add_f32_e32 v70, 1.0, v70
	v_fma_f32 v95, -v95, v98, v97
	v_add_f32_e32 v76, 1.0, v76
	v_div_fmas_f32 v95, v95, v96, v98
	v_add_f32_e32 v82, 1.0, v82
	v_div_scale_f32 v103, vcc, 1.0, v100, 1.0
	v_div_scale_f32 v65, s[4:5], v64, v64, 1.0
	v_mul_f32_e32 v104, v103, v102
	v_div_scale_f32 v71, s[4:5], v70, v70, 1.0
	v_fma_f32 v105, -v101, v104, v103
	v_div_scale_f32 v77, s[4:5], v76, v76, 1.0
	v_fmac_f32_e32 v104, v105, v102
	v_div_scale_f32 v83, s[4:5], v82, v82, 1.0
	v_fma_f32 v101, -v101, v104, v103
	v_rcp_f32_e32 v66, v65
	v_div_fmas_f32 v101, v101, v102, v104
	v_rcp_f32_e32 v72, v71
	v_div_scale_f32 v109, vcc, 1.0, v106, 1.0
	v_rcp_f32_e32 v78, v77
	v_mul_f32_e32 v110, v109, v108
	v_rcp_f32_e32 v84, v83
	v_fma_f32 v111, -v107, v110, v109
	v_fma_f32 v69, -v65, v66, 1.0
	v_fmac_f32_e32 v110, v111, v108
	v_fma_f32 v75, -v71, v72, 1.0
	v_fma_f32 v107, -v107, v110, v109
	v_fma_f32 v81, -v77, v78, 1.0
	v_div_fmas_f32 v107, v107, v108, v110
	v_fma_f32 v87, -v83, v84, 1.0
	v_fmac_f32_e32 v66, v69, v66
	v_fmac_f32_e32 v72, v75, v72
	v_fmac_f32_e32 v78, v81, v78
	v_fmac_f32_e32 v84, v87, v84
	v_div_fixup_f32 v89, v89, v88, 1.0
	v_div_fixup_f32 v95, v95, v94, 1.0
	v_div_fixup_f32 v101, v101, v100, 1.0
	v_div_fixup_f32 v107, v107, v106, 1.0
	v_mul_f32_e32 v89, v60, v89
	v_mul_f32_e32 v95, v61, v95
	v_mul_f32_e32 v101, v62, v101
	v_mul_f32_e32 v107, v63, v107
	v_mul_f32_e32 v89, v44, v89
	v_mul_f32_e32 v95, v45, v95
	v_mul_f32_e32 v101, v46, v101
	v_mul_f32_e32 v107, v47, v107
	v_cvt_pk_bf16_f32 v89, v89, v89
	v_cvt_pk_bf16_f32 v95, v95, v95
	v_cvt_pk_bf16_f32 v101, v101, v101
	v_cvt_pk_bf16_f32 v107, v107, v107
	ds_write_b16 v112, v89 offset:1536
	ds_write_b16 v112, v95 offset:1600
	ds_write_b16 v112, v101 offset:1664
	ds_write_b16 v112, v107 offset:1728
	ds_read_b128 v[120:123], v113
	ds_read_b128 v[124:127], v113 offset:1024
	v_div_scale_f32 v67, vcc, 1.0, v64, 1.0
	v_mul_f32_e32 v88, 0xbfb8aa3b, v20
	v_mul_f32_e32 v68, v67, v66
	v_mul_f32_e32 v94, 0xbfb8aa3b, v21
	v_fma_f32 v69, -v65, v68, v67
	v_mul_f32_e32 v100, 0xbfb8aa3b, v22
	v_fmac_f32_e32 v68, v69, v66
	v_mul_f32_e32 v106, 0xbfb8aa3b, v23
	v_fma_f32 v65, -v65, v68, v67
	v_exp_f32_e32 v88, v88
	v_div_fmas_f32 v65, v65, v66, v68
	v_exp_f32_e32 v94, v94
	v_div_scale_f32 v73, vcc, 1.0, v70, 1.0
	v_exp_f32_e32 v100, v100
	v_mul_f32_e32 v74, v73, v72
	v_exp_f32_e32 v106, v106
	v_fma_f32 v75, -v71, v74, v73
	v_add_f32_e32 v88, 1.0, v88
	v_fmac_f32_e32 v74, v75, v72
	v_add_f32_e32 v94, 1.0, v94
	v_fma_f32 v71, -v71, v74, v73
	v_add_f32_e32 v100, 1.0, v100
	v_div_fmas_f32 v71, v71, v72, v74
	v_add_f32_e32 v106, 1.0, v106
	v_div_scale_f32 v79, vcc, 1.0, v76, 1.0
	v_div_scale_f32 v89, s[4:5], v88, v88, 1.0
	v_mul_f32_e32 v80, v79, v78
	v_div_scale_f32 v95, s[4:5], v94, v94, 1.0
	v_fma_f32 v81, -v77, v80, v79
	v_div_scale_f32 v101, s[4:5], v100, v100, 1.0
	v_fmac_f32_e32 v80, v81, v78
	v_div_scale_f32 v107, s[4:5], v106, v106, 1.0
	v_fma_f32 v77, -v77, v80, v79
	v_rcp_f32_e32 v90, v89
	v_div_fmas_f32 v77, v77, v78, v80
	v_rcp_f32_e32 v96, v95
	v_div_scale_f32 v85, vcc, 1.0, v82, 1.0
	v_rcp_f32_e32 v102, v101
	v_mul_f32_e32 v86, v85, v84
	v_rcp_f32_e32 v108, v107
	v_fma_f32 v87, -v83, v86, v85
	v_fma_f32 v93, -v89, v90, 1.0
	v_fmac_f32_e32 v86, v87, v84
	v_fma_f32 v99, -v95, v96, 1.0
	v_fma_f32 v83, -v83, v86, v85
	v_fma_f32 v105, -v101, v102, 1.0
	v_div_fmas_f32 v83, v83, v84, v86
	v_fma_f32 v111, -v107, v108, 1.0
	v_fmac_f32_e32 v90, v93, v90
	v_fmac_f32_e32 v96, v99, v96
	v_fmac_f32_e32 v102, v105, v102
	v_fmac_f32_e32 v108, v111, v108
	s_waitcnt lgkmcnt(0)
	global_store_dwordx4 v114, v[120:123], s[98:99]
	s_add_u32 s98, s98, 0x16000
	s_addc_u32 s99, s99, 0
	global_store_dwordx4 v114, v[124:127], s[98:99]
	s_add_u32 s98, s98, 0x16000
	s_addc_u32 s99, s99, 0
	v_div_fixup_f32 v65, v65, v64, 1.0
	v_div_fixup_f32 v71, v71, v70, 1.0
	v_div_fixup_f32 v77, v77, v76, 1.0
	v_div_fixup_f32 v83, v83, v82, 1.0
	v_mul_f32_e32 v65, v16, v65
	v_mul_f32_e32 v71, v17, v71
	v_mul_f32_e32 v77, v18, v77
	v_mul_f32_e32 v83, v19, v83
	v_mul_f32_e32 v65, v0, v65
	v_mul_f32_e32 v71, v1, v71
	v_mul_f32_e32 v77, v2, v77
	v_mul_f32_e32 v83, v3, v83
	v_cvt_pk_bf16_f32 v65, v65, v65
	v_cvt_pk_bf16_f32 v71, v71, v71
	v_cvt_pk_bf16_f32 v77, v77, v77
	v_cvt_pk_bf16_f32 v83, v83, v83
	ds_write_b16 v112, v65
	ds_write_b16 v112, v71 offset:64
	ds_write_b16 v112, v77 offset:128
	ds_write_b16 v112, v83 offset:192
	v_div_scale_f32 v91, vcc, 1.0, v88, 1.0
	v_mul_f32_e32 v64, 0xbfb8aa3b, v24
	v_mul_f32_e32 v92, v91, v90
	v_mul_f32_e32 v70, 0xbfb8aa3b, v25
	v_fma_f32 v93, -v89, v92, v91
	v_mul_f32_e32 v76, 0xbfb8aa3b, v26
	v_fmac_f32_e32 v92, v93, v90
	v_mul_f32_e32 v82, 0xbfb8aa3b, v27
	v_fma_f32 v89, -v89, v92, v91
	v_exp_f32_e32 v64, v64
	v_div_fmas_f32 v89, v89, v90, v92
	v_exp_f32_e32 v70, v70
	v_div_scale_f32 v97, vcc, 1.0, v94, 1.0
	v_exp_f32_e32 v76, v76
	v_mul_f32_e32 v98, v97, v96
	v_exp_f32_e32 v82, v82
	v_fma_f32 v99, -v95, v98, v97
	v_add_f32_e32 v64, 1.0, v64
	v_fmac_f32_e32 v98, v99, v96
	v_add_f32_e32 v70, 1.0, v70
	v_fma_f32 v95, -v95, v98, v97
	v_add_f32_e32 v76, 1.0, v76
	v_div_fmas_f32 v95, v95, v96, v98
	v_add_f32_e32 v82, 1.0, v82
	v_div_scale_f32 v103, vcc, 1.0, v100, 1.0
	v_div_scale_f32 v65, s[4:5], v64, v64, 1.0
	v_mul_f32_e32 v104, v103, v102
	v_div_scale_f32 v71, s[4:5], v70, v70, 1.0
	v_fma_f32 v105, -v101, v104, v103
	v_div_scale_f32 v77, s[4:5], v76, v76, 1.0
	v_fmac_f32_e32 v104, v105, v102
	v_div_scale_f32 v83, s[4:5], v82, v82, 1.0
	v_fma_f32 v101, -v101, v104, v103
	v_rcp_f32_e32 v66, v65
	v_div_fmas_f32 v101, v101, v102, v104
	v_rcp_f32_e32 v72, v71
	v_div_scale_f32 v109, vcc, 1.0, v106, 1.0
	v_rcp_f32_e32 v78, v77
	v_mul_f32_e32 v110, v109, v108
	v_rcp_f32_e32 v84, v83
	v_fma_f32 v111, -v107, v110, v109
	v_fma_f32 v69, -v65, v66, 1.0
	v_fmac_f32_e32 v110, v111, v108
	v_fma_f32 v75, -v71, v72, 1.0
	v_fma_f32 v107, -v107, v110, v109
	v_fma_f32 v81, -v77, v78, 1.0
	v_div_fmas_f32 v107, v107, v108, v110
	v_fma_f32 v87, -v83, v84, 1.0
	v_fmac_f32_e32 v66, v69, v66
	v_fmac_f32_e32 v72, v75, v72
	v_fmac_f32_e32 v78, v81, v78
	v_fmac_f32_e32 v84, v87, v84
	v_div_fixup_f32 v89, v89, v88, 1.0
	v_div_fixup_f32 v95, v95, v94, 1.0
	v_div_fixup_f32 v101, v101, v100, 1.0
	v_div_fixup_f32 v107, v107, v106, 1.0
	v_mul_f32_e32 v89, v20, v89
	v_mul_f32_e32 v95, v21, v95
	v_mul_f32_e32 v101, v22, v101
	v_mul_f32_e32 v107, v23, v107
	v_mul_f32_e32 v89, v4, v89
	v_mul_f32_e32 v95, v5, v95
	v_mul_f32_e32 v101, v6, v101
	v_mul_f32_e32 v107, v7, v107
	v_cvt_pk_bf16_f32 v89, v89, v89
	v_cvt_pk_bf16_f32 v95, v95, v95
	v_cvt_pk_bf16_f32 v101, v101, v101
	v_cvt_pk_bf16_f32 v107, v107, v107
	ds_write_b16 v112, v89 offset:512
	ds_write_b16 v112, v95 offset:576
	ds_write_b16 v112, v101 offset:640
	ds_write_b16 v112, v107 offset:704
	v_div_scale_f32 v67, vcc, 1.0, v64, 1.0
	v_mul_f32_e32 v88, 0xbfb8aa3b, v28
	v_mul_f32_e32 v68, v67, v66
	v_mul_f32_e32 v94, 0xbfb8aa3b, v29
	v_fma_f32 v69, -v65, v68, v67
	v_mul_f32_e32 v100, 0xbfb8aa3b, v30
	v_fmac_f32_e32 v68, v69, v66
	v_mul_f32_e32 v106, 0xbfb8aa3b, v31
	v_fma_f32 v65, -v65, v68, v67
	v_exp_f32_e32 v88, v88
	v_div_fmas_f32 v65, v65, v66, v68
	v_exp_f32_e32 v94, v94
	v_div_scale_f32 v73, vcc, 1.0, v70, 1.0
	v_exp_f32_e32 v100, v100
	v_mul_f32_e32 v74, v73, v72
	v_exp_f32_e32 v106, v106
	v_fma_f32 v75, -v71, v74, v73
	v_add_f32_e32 v88, 1.0, v88
	v_fmac_f32_e32 v74, v75, v72
	v_add_f32_e32 v94, 1.0, v94
	v_fma_f32 v71, -v71, v74, v73
	v_add_f32_e32 v100, 1.0, v100
	v_div_fmas_f32 v71, v71, v72, v74
	v_add_f32_e32 v106, 1.0, v106
	v_div_scale_f32 v79, vcc, 1.0, v76, 1.0
	v_div_scale_f32 v89, s[4:5], v88, v88, 1.0
	v_mul_f32_e32 v80, v79, v78
	v_div_scale_f32 v95, s[4:5], v94, v94, 1.0
	v_fma_f32 v81, -v77, v80, v79
	v_div_scale_f32 v101, s[4:5], v100, v100, 1.0
	v_fmac_f32_e32 v80, v81, v78
	v_div_scale_f32 v107, s[4:5], v106, v106, 1.0
	v_fma_f32 v77, -v77, v80, v79
	v_rcp_f32_e32 v90, v89
	v_div_fmas_f32 v77, v77, v78, v80
	v_rcp_f32_e32 v96, v95
	v_div_scale_f32 v85, vcc, 1.0, v82, 1.0
	v_rcp_f32_e32 v102, v101
	v_mul_f32_e32 v86, v85, v84
	v_rcp_f32_e32 v108, v107
	v_fma_f32 v87, -v83, v86, v85
	v_fma_f32 v93, -v89, v90, 1.0
	v_fmac_f32_e32 v86, v87, v84
	v_fma_f32 v99, -v95, v96, 1.0
	v_fma_f32 v83, -v83, v86, v85
	v_fma_f32 v105, -v101, v102, 1.0
	v_div_fmas_f32 v83, v83, v84, v86
	v_fma_f32 v111, -v107, v108, 1.0
	v_fmac_f32_e32 v90, v93, v90
	v_fmac_f32_e32 v96, v99, v96
	v_fmac_f32_e32 v102, v105, v102
	v_fmac_f32_e32 v108, v111, v108
	v_div_fixup_f32 v65, v65, v64, 1.0
	v_div_fixup_f32 v71, v71, v70, 1.0
	v_div_fixup_f32 v77, v77, v76, 1.0
	v_div_fixup_f32 v83, v83, v82, 1.0
	v_mul_f32_e32 v65, v24, v65
	v_mul_f32_e32 v71, v25, v71
	v_mul_f32_e32 v77, v26, v77
	v_mul_f32_e32 v83, v27, v83
	v_mul_f32_e32 v65, v8, v65
	v_mul_f32_e32 v71, v9, v71
	v_mul_f32_e32 v77, v10, v77
	v_mul_f32_e32 v83, v11, v83
	v_cvt_pk_bf16_f32 v65, v65, v65
	v_cvt_pk_bf16_f32 v71, v71, v71
	v_cvt_pk_bf16_f32 v77, v77, v77
	v_cvt_pk_bf16_f32 v83, v83, v83
	ds_write_b16 v112, v65 offset:1024
	ds_write_b16 v112, v71 offset:1088
	ds_write_b16 v112, v77 offset:1152
	ds_write_b16 v112, v83 offset:1216
	v_div_scale_f32 v91, vcc, 1.0, v88, 1.0
	v_mul_f32_e32 v92, v91, v90
	v_fma_f32 v93, -v89, v92, v91
	v_fmac_f32_e32 v92, v93, v90
	v_fma_f32 v89, -v89, v92, v91
	v_div_fmas_f32 v89, v89, v90, v92
	v_div_scale_f32 v97, vcc, 1.0, v94, 1.0
	v_mul_f32_e32 v98, v97, v96
	v_fma_f32 v99, -v95, v98, v97
	v_fmac_f32_e32 v98, v99, v96
	v_fma_f32 v95, -v95, v98, v97
	v_div_fmas_f32 v95, v95, v96, v98
	v_div_scale_f32 v103, vcc, 1.0, v100, 1.0
	v_mul_f32_e32 v104, v103, v102
	v_fma_f32 v105, -v101, v104, v103
	v_fmac_f32_e32 v104, v105, v102
	v_fma_f32 v101, -v101, v104, v103
	v_div_fmas_f32 v101, v101, v102, v104
	v_div_scale_f32 v109, vcc, 1.0, v106, 1.0
	v_mul_f32_e32 v110, v109, v108
	v_fma_f32 v111, -v107, v110, v109
	v_fmac_f32_e32 v110, v111, v108
	v_fma_f32 v107, -v107, v110, v109
	v_div_fmas_f32 v107, v107, v108, v110
	v_div_fixup_f32 v89, v89, v88, 1.0
	v_div_fixup_f32 v95, v95, v94, 1.0
	v_div_fixup_f32 v101, v101, v100, 1.0
	v_div_fixup_f32 v107, v107, v106, 1.0
	v_mul_f32_e32 v89, v28, v89
	v_mul_f32_e32 v95, v29, v95
	v_mul_f32_e32 v101, v30, v101
	v_mul_f32_e32 v107, v31, v107
	v_mul_f32_e32 v89, v12, v89
	v_mul_f32_e32 v95, v13, v95
	v_mul_f32_e32 v101, v14, v101
	v_mul_f32_e32 v107, v15, v107
	v_cvt_pk_bf16_f32 v89, v89, v89
	v_cvt_pk_bf16_f32 v95, v95, v95
	v_cvt_pk_bf16_f32 v101, v101, v101
	v_cvt_pk_bf16_f32 v107, v107, v107
	ds_write_b16 v112, v89 offset:1536
	ds_write_b16 v112, v95 offset:1600
	ds_write_b16 v112, v101 offset:1664
	ds_write_b16 v112, v107 offset:1728
	ds_read_b128 v[120:123], v113
	ds_read_b128 v[124:127], v113 offset:1024
	s_waitcnt lgkmcnt(0)
	global_store_dwordx4 v114, v[120:123], s[98:99]
	s_add_u32 s98, s98, 0x16000
	s_addc_u32 s99, s99, 0
	global_store_dwordx4 v114, v[124:127], s[98:99]
	s_add_u32 s98, s98, 0x16000
	s_addc_u32 s99, s99, 0
	s_add_i32 s47, s47, s92
	s_cmpk_gt_i32 s47, 0xfff
	s_cbranch_scc1 .LBB0_2292

.LBB0_2292:
	s_cmp_ge_u32 s33, 0x100
	s_cbranch_scc1 .Lffh6_skip
	s_lshr_b32 s47, s33, 1
	s_addk_i32 s47, 0x1000
	s_and_b32 s98, s47, 7
	s_bfe_u32 s99, s47, 0x60003
	s_lshr_b32 s100, s47, 9
	s_lshl_b32 s100, s100, 6
	s_add_u32 s99, s99, s100
	s_mul_hi_u32 s100, s99, 0xaaaaaaab
	s_lshr_b32 s100, s100, 3
	s_mul_i32 s101, s100, 12
	s_sub_u32 s99, s99, s101
	s_mul_i32 s98, s98, 12
	s_add_u32 s98, s98, s99
	s_lshl_b32 s48, s98, 7
	s_lshl_b32 s49, s100, 7
	s_and_b32 s98, s33, 1
	s_lshl_b32 s98, s98, 6
	s_add_u32 s48, s48, s98
	v_lshl_or_b32 v32, v183, 3, v191
	v_and_b32_e32 v33, 63, v32
	v_lshrrev_b32_e32 v34, 3, v33
	v_lshrrev_b32_e32 v35, 4, v33
	v_xor_b32_e32 v35, v35, v33
	v_and_b32_e32 v35, 7, v35
	v_lshlrev_b32_e32 v35, 4, v35
	s_movk_i32 s101, 0x800
	v_mad_u32_u24 v68, v34, s101, v35
	v_xor_b32_e32 v36, 64, v68
	v_add_u32_e32 v69, 0x3c00, v36
	v_add_u32_e32 v70, 0x7800, v68
	v_add_u32_e32 v71, 0xb400, v36
	v_and_b32_e32 v37, 31, v32
	v_bfe_u32 v38, v32, 5, 1
	v_bfe_u32 v39, v32, 1, 3
	v_xor_b32_e32 v39, v39, v38
	v_lshlrev_b32_e32 v39, 4, v39
	v_bfe_u32 v40, v32, 7, 1
	v_lshl_or_b32 v40, v40, 6, v37
	v_lshl_add_u32 v72, v40, 7, v39
	v_bfe_u32 v41, v32, 6, 1
	v_lshl_or_b32 v41, v41, 5, v37
	v_lshl_add_u32 v76, v41, 7, v39
	v_add_u32_e32 v76, 0x4000, v76
	v_xor_b32_e32 v73, 32, v72
	v_xor_b32_e32 v77, 32, v76
	v_xor_b32_e32 v74, 64, v72
	v_xor_b32_e32 v78, 64, v76
	v_xor_b32_e32 v75, 96, v72
	v_xor_b32_e32 v79, 96, v76
	v_lshrrev_b32_e32 v42, 6, v32
	s_nop 0
	v_readfirstlane_b32 s47, v42
	s_nop 3
	s_lshl_b32 s98, s47, 12
	s_lshl_b32 s99, s47, 11
	s_add_u32 s99, s99, 0x4000
	s_lshl_b32 s101, s47, 5
	s_add_u32 s101, s101, s49
	s_mul_i32 s101, s101, 0x800
	s_add_u32 s101, s101, 0x1640000
	s_add_u32 s4, s90, s101
	s_addc_u32 s5, s91, 0
	s_lshl_b32 s101, s47, 4
	s_add_u32 s101, s101, s48
	s_mul_i32 s101, s101, 0x800
	s_add_u32 s101, s101, 0xb171900
	s_add_u32 s6, s90, s101
	s_addc_u32 s7, s91, 0
	s_add_u32 m0, s98, 0x0
	s_nop 0
	global_load_lds_dwordx4 v68, s[4:5] offset:0
	global_load_lds_dwordx4 v69, s[4:5] offset:1024
	global_load_lds_dwordx4 v70, s[4:5] offset:2048
	global_load_lds_dwordx4 v71, s[4:5] offset:3072
	s_add_u32 m0, s99, 0x0
	s_nop 0
	global_load_lds_dwordx4 v68, s[6:7] offset:0
	global_load_lds_dwordx4 v69, s[6:7] offset:1024
	s_add_u32 s4, s4, 0x80
	s_addc_u32 s5, s5, 0
	s_add_u32 s6, s6, 0x80
	s_addc_u32 s7, s7, 0
	s_add_u32 m0, s98, 0x8000
	s_nop 0
	global_load_lds_dwordx4 v68, s[4:5] offset:0
	global_load_lds_dwordx4 v69, s[4:5] offset:1024
	global_load_lds_dwordx4 v70, s[4:5] offset:2048
	global_load_lds_dwordx4 v71, s[4:5] offset:3072
	s_add_u32 m0, s99, 0x8000
	s_nop 0
	global_load_lds_dwordx4 v68, s[6:7] offset:0
	global_load_lds_dwordx4 v69, s[6:7] offset:1024
	s_add_u32 s4, s4, 0x80
	s_addc_u32 s5, s5, 0
	s_add_u32 s6, s6, 0x80
	s_addc_u32 s7, s7, 0
	v_mov_b32_e32 v0, 0
	v_mov_b32_e32 v1, 0
	v_mov_b32_e32 v2, 0
	v_mov_b32_e32 v3, 0
	v_mov_b32_e32 v4, 0
	v_mov_b32_e32 v5, 0
	v_mov_b32_e32 v6, 0
	v_mov_b32_e32 v7, 0
	v_mov_b32_e32 v8, 0
	v_mov_b32_e32 v9, 0
	v_mov_b32_e32 v10, 0
	v_mov_b32_e32 v11, 0
	v_mov_b32_e32 v12, 0
	v_mov_b32_e32 v13, 0
	v_mov_b32_e32 v14, 0
	v_mov_b32_e32 v15, 0
	v_mov_b32_e32 v16, 0
	v_mov_b32_e32 v17, 0
	v_mov_b32_e32 v18, 0
	v_mov_b32_e32 v19, 0
	v_mov_b32_e32 v20, 0
	v_mov_b32_e32 v21, 0
	v_mov_b32_e32 v22, 0
	v_mov_b32_e32 v23, 0
	v_mov_b32_e32 v24, 0
	v_mov_b32_e32 v25, 0
	v_mov_b32_e32 v26, 0
	v_mov_b32_e32 v27, 0
	v_mov_b32_e32 v28, 0
	v_mov_b32_e32 v29, 0
	v_mov_b32_e32 v30, 0
	v_mov_b32_e32 v31, 0
	s_movk_i32 s100, 7
	s_waitcnt vmcnt(6)
.Lgfh6_loop:
	s_waitcnt vmcnt(6)
	s_barrier
	ds_read_b128 v[32:35], v72 offset:0
	ds_read_b128 v[40:43], v76 offset:0
	ds_read_b128 v[36:39], v72 offset:4096
	ds_read_b128 v[44:47], v73 offset:0
	ds_read_b128 v[52:55], v77 offset:0
	ds_read_b128 v[48:51], v73 offset:4096
	s_waitcnt lgkmcnt(3)
	v_mfma_f32_32x32x16_bf16 v[0:15], v[40:43], v[32:35], v[0:15]
	ds_read_b128 v[56:59], v74 offset:0
	ds_read_b128 v[64:67], v78 offset:0
	v_mfma_f32_32x32x16_bf16 v[16:31], v[40:43], v[36:39], v[16:31]
	ds_read_b128 v[60:63], v74 offset:4096
	s_waitcnt lgkmcnt(3)
	v_mfma_f32_32x32x16_bf16 v[0:15], v[52:55], v[44:47], v[0:15]
	ds_read_b128 v[32:35], v75 offset:0
	ds_read_b128 v[40:43], v79 offset:0
	v_mfma_f32_32x32x16_bf16 v[16:31], v[52:55], v[48:51], v[16:31]
	ds_read_b128 v[36:39], v75 offset:4096
	s_waitcnt lgkmcnt(3)
	v_mfma_f32_32x32x16_bf16 v[0:15], v[64:67], v[56:59], v[0:15]
	v_mfma_f32_32x32x16_bf16 v[16:31], v[64:67], v[60:63], v[16:31]
	s_waitcnt lgkmcnt(0)
	v_mfma_f32_32x32x16_bf16 v[0:15], v[40:43], v[32:35], v[0:15]
	v_mfma_f32_32x32x16_bf16 v[16:31], v[40:43], v[36:39], v[16:31]
	s_barrier
	s_add_u32 m0, s98, 0x0
	s_nop 0
	global_load_lds_dwordx4 v68, s[4:5] offset:0
	global_load_lds_dwordx4 v69, s[4:5] offset:1024
	global_load_lds_dwordx4 v70, s[4:5] offset:2048
	global_load_lds_dwordx4 v71, s[4:5] offset:3072
	s_add_u32 m0, s99, 0x0
	s_nop 0
	global_load_lds_dwordx4 v68, s[6:7] offset:0
	global_load_lds_dwordx4 v69, s[6:7] offset:1024
	s_add_u32 s4, s4, 0x80
	s_addc_u32 s5, s5, 0
	s_add_u32 s6, s6, 0x80
	s_addc_u32 s7, s7, 0
	s_waitcnt vmcnt(6)
	s_barrier
	ds_read_b128 v[32:35], v72 offset:32768
	ds_read_b128 v[40:43], v76 offset:32768
	ds_read_b128 v[36:39], v72 offset:36864
	ds_read_b128 v[44:47], v73 offset:32768
	ds_read_b128 v[52:55], v77 offset:32768
	ds_read_b128 v[48:51], v73 offset:36864
	s_waitcnt lgkmcnt(3)
	v_mfma_f32_32x32x16_bf16 v[0:15], v[40:43], v[32:35], v[0:15]
	ds_read_b128 v[56:59], v74 offset:32768
	ds_read_b128 v[64:67], v78 offset:32768
	v_mfma_f32_32x32x16_bf16 v[16:31], v[40:43], v[36:39], v[16:31]
	ds_read_b128 v[60:63], v74 offset:36864
	s_waitcnt lgkmcnt(3)
	v_mfma_f32_32x32x16_bf16 v[0:15], v[52:55], v[44:47], v[0:15]
	ds_read_b128 v[32:35], v75 offset:32768
	ds_read_b128 v[40:43], v79 offset:32768
	v_mfma_f32_32x32x16_bf16 v[16:31], v[52:55], v[48:51], v[16:31]
	ds_read_b128 v[36:39], v75 offset:36864
	s_waitcnt lgkmcnt(3)
	v_mfma_f32_32x32x16_bf16 v[0:15], v[64:67], v[56:59], v[0:15]
	v_mfma_f32_32x32x16_bf16 v[16:31], v[64:67], v[60:63], v[16:31]
	s_waitcnt lgkmcnt(0)
	v_mfma_f32_32x32x16_bf16 v[0:15], v[40:43], v[32:35], v[0:15]
	v_mfma_f32_32x32x16_bf16 v[16:31], v[40:43], v[36:39], v[16:31]
	s_barrier
	s_add_u32 m0, s98, 0x8000
	s_nop 0
	global_load_lds_dwordx4 v68, s[4:5] offset:0
	global_load_lds_dwordx4 v69, s[4:5] offset:1024
	global_load_lds_dwordx4 v70, s[4:5] offset:2048
	global_load_lds_dwordx4 v71, s[4:5] offset:3072
	s_add_u32 m0, s99, 0x8000
	s_nop 0
	global_load_lds_dwordx4 v68, s[6:7] offset:0
	global_load_lds_dwordx4 v69, s[6:7] offset:1024
	s_add_u32 s4, s4, 0x80
	s_addc_u32 s5, s5, 0
	s_add_u32 s6, s6, 0x80
	s_addc_u32 s7, s7, 0
	s_sub_u32 s100, s100, 1
	s_cmp_lg_u32 s100, 0
	s_cbranch_scc1 .Lgfh6_loop
	s_waitcnt vmcnt(6)
	s_barrier
	ds_read_b128 v[32:35], v72 offset:0
	ds_read_b128 v[40:43], v76 offset:0
	ds_read_b128 v[36:39], v72 offset:4096
	ds_read_b128 v[44:47], v73 offset:0
	ds_read_b128 v[52:55], v77 offset:0
	ds_read_b128 v[48:51], v73 offset:4096
	s_waitcnt lgkmcnt(3)
	v_mfma_f32_32x32x16_bf16 v[0:15], v[40:43], v[32:35], v[0:15]
	ds_read_b128 v[56:59], v74 offset:0
	ds_read_b128 v[64:67], v78 offset:0
	v_mfma_f32_32x32x16_bf16 v[16:31], v[40:43], v[36:39], v[16:31]
	ds_read_b128 v[60:63], v74 offset:4096
	s_waitcnt lgkmcnt(3)
	v_mfma_f32_32x32x16_bf16 v[0:15], v[52:55], v[44:47], v[0:15]
	ds_read_b128 v[32:35], v75 offset:0
	ds_read_b128 v[40:43], v79 offset:0
	v_mfma_f32_32x32x16_bf16 v[16:31], v[52:55], v[48:51], v[16:31]
	ds_read_b128 v[36:39], v75 offset:4096
	s_waitcnt lgkmcnt(3)
	v_mfma_f32_32x32x16_bf16 v[0:15], v[64:67], v[56:59], v[0:15]
	v_mfma_f32_32x32x16_bf16 v[16:31], v[64:67], v[60:63], v[16:31]
	s_waitcnt lgkmcnt(0)
	v_mfma_f32_32x32x16_bf16 v[0:15], v[40:43], v[32:35], v[0:15]
	v_mfma_f32_32x32x16_bf16 v[16:31], v[40:43], v[36:39], v[16:31]
	s_barrier
	s_waitcnt vmcnt(0)
	s_barrier
	ds_read_b128 v[32:35], v72 offset:32768
	ds_read_b128 v[40:43], v76 offset:32768
	ds_read_b128 v[36:39], v72 offset:36864
	ds_read_b128 v[44:47], v73 offset:32768
	ds_read_b128 v[52:55], v77 offset:32768
	ds_read_b128 v[48:51], v73 offset:36864
	s_waitcnt lgkmcnt(3)
	v_mfma_f32_32x32x16_bf16 v[0:15], v[40:43], v[32:35], v[0:15]
	ds_read_b128 v[56:59], v74 offset:32768
	ds_read_b128 v[64:67], v78 offset:32768
	v_mfma_f32_32x32x16_bf16 v[16:31], v[40:43], v[36:39], v[16:31]
	ds_read_b128 v[60:63], v74 offset:36864
	s_waitcnt lgkmcnt(3)
	v_mfma_f32_32x32x16_bf16 v[0:15], v[52:55], v[44:47], v[0:15]
	ds_read_b128 v[32:35], v75 offset:32768
	ds_read_b128 v[40:43], v79 offset:32768
	v_mfma_f32_32x32x16_bf16 v[16:31], v[52:55], v[48:51], v[16:31]
	ds_read_b128 v[36:39], v75 offset:36864
	s_waitcnt lgkmcnt(3)
	v_mfma_f32_32x32x16_bf16 v[0:15], v[64:67], v[56:59], v[0:15]
	v_mfma_f32_32x32x16_bf16 v[16:31], v[64:67], v[60:63], v[16:31]
	s_waitcnt lgkmcnt(0)
	v_mfma_f32_32x32x16_bf16 v[0:15], v[40:43], v[32:35], v[0:15]
	v_mfma_f32_32x32x16_bf16 v[16:31], v[40:43], v[36:39], v[16:31]
	s_barrier
	s_nop 7
	s_nop 7
	s_branch .Lffh6_epi
.Lffh6_epi:
	v_lshl_or_b32 v115, v183, 3, v191
	v_lshrrev_b32_e32 v116, 6, v115
	v_and_b32_e32 v117, 63, v115
	v_lshlrev_b32_e32 v113, 11, v116
	v_add_u32_e32 v113, 0x10000, v113
	v_readfirstlane_b32 s100, v116
	v_and_b32_e32 v112, 31, v117
	v_lshl_add_u32 v112, v112, 1, v113
	v_lshrrev_b32_e32 v116, 5, v117
	v_lshl_add_u32 v112, v116, 8, v112
	v_lshl_add_u32 v113, v117, 4, v113
	v_lshrrev_b32_e32 v116, 2, v117
	v_mul_u32_u24_e32 v116, 0x1600, v116
	v_and_b32_e32 v114, 3, v117
	v_lshl_add_u32 v114, v114, 4, v116
	s_and_b32 s101, s100, 1
	s_lshl_b32 s101, s101, 5
	s_add_u32 s101, s101, s48
	s_mul_i32 s101, s101, 0x1600
	s_lshr_b32 s100, s100, 1
	s_lshl_b32 s100, s100, 6
	s_add_u32 s100, s100, s49
	s_add_u32 s101, s101, s100
	s_add_u32 s98, s90, 0x3971900
	s_addc_u32 s99, s91, 0
	s_add_u32 s98, s98, s101
	s_addc_u32 s99, s99, 0
	v_mul_f32_e32 v64, 0xbfb8aa3b, v0
	v_mul_f32_e32 v70, 0xbfb8aa3b, v1
	v_mul_f32_e32 v76, 0xbfb8aa3b, v2
	v_mul_f32_e32 v82, 0xbfb8aa3b, v3
	v_exp_f32_e32 v64, v64
	v_exp_f32_e32 v70, v70
	v_exp_f32_e32 v76, v76
	v_exp_f32_e32 v82, v82
	v_add_f32_e32 v64, 1.0, v64
	v_add_f32_e32 v70, 1.0, v70
	v_add_f32_e32 v76, 1.0, v76
	v_add_f32_e32 v82, 1.0, v82
	v_div_scale_f32 v65, s[4:5], v64, v64, 1.0
	v_div_scale_f32 v71, s[4:5], v70, v70, 1.0
	v_div_scale_f32 v77, s[4:5], v76, v76, 1.0
	v_div_scale_f32 v83, s[4:5], v82, v82, 1.0
	v_rcp_f32_e32 v66, v65
	v_rcp_f32_e32 v72, v71
	v_rcp_f32_e32 v78, v77
	v_rcp_f32_e32 v84, v83
	v_fma_f32 v69, -v65, v66, 1.0
	v_fma_f32 v75, -v71, v72, 1.0
	v_fma_f32 v81, -v77, v78, 1.0
	v_fma_f32 v87, -v83, v84, 1.0
	v_fmac_f32_e32 v66, v69, v66
	v_fmac_f32_e32 v72, v75, v72
	v_fmac_f32_e32 v78, v81, v78
	v_fmac_f32_e32 v84, v87, v84
	v_div_scale_f32 v67, vcc, 1.0, v64, 1.0
	v_mul_f32_e32 v88, 0xbfb8aa3b, v4
	v_mul_f32_e32 v68, v67, v66
	v_mul_f32_e32 v94, 0xbfb8aa3b, v5
	v_fma_f32 v69, -v65, v68, v67
	v_mul_f32_e32 v100, 0xbfb8aa3b, v6
	v_fmac_f32_e32 v68, v69, v66
	v_mul_f32_e32 v106, 0xbfb8aa3b, v7
	v_fma_f32 v65, -v65, v68, v67
	v_exp_f32_e32 v88, v88
	v_div_fmas_f32 v65, v65, v66, v68
	v_exp_f32_e32 v94, v94
	v_div_scale_f32 v73, vcc, 1.0, v70, 1.0
	v_exp_f32_e32 v100, v100
	v_mul_f32_e32 v74, v73, v72
	v_exp_f32_e32 v106, v106
	v_fma_f32 v75, -v71, v74, v73
	v_add_f32_e32 v88, 1.0, v88
	v_fmac_f32_e32 v74, v75, v72
	v_add_f32_e32 v94, 1.0, v94
	v_fma_f32 v71, -v71, v74, v73
	v_add_f32_e32 v100, 1.0, v100
	v_div_fmas_f32 v71, v71, v72, v74
	v_add_f32_e32 v106, 1.0, v106
	v_div_scale_f32 v79, vcc, 1.0, v76, 1.0
	v_div_scale_f32 v89, s[4:5], v88, v88, 1.0
	v_mul_f32_e32 v80, v79, v78
	v_div_scale_f32 v95, s[4:5], v94, v94, 1.0
	v_fma_f32 v81, -v77, v80, v79
	v_div_scale_f32 v101, s[4:5], v100, v100, 1.0
	v_fmac_f32_e32 v80, v81, v78
	v_div_scale_f32 v107, s[4:5], v106, v106, 1.0
	v_fma_f32 v77, -v77, v80, v79
	v_rcp_f32_e32 v90, v89
	v_div_fmas_f32 v77, v77, v78, v80
	v_rcp_f32_e32 v96, v95
	v_div_scale_f32 v85, vcc, 1.0, v82, 1.0
	v_rcp_f32_e32 v102, v101
	v_mul_f32_e32 v86, v85, v84
	v_rcp_f32_e32 v108, v107
	v_fma_f32 v87, -v83, v86, v85
	v_fma_f32 v93, -v89, v90, 1.0
	v_fmac_f32_e32 v86, v87, v84
	v_fma_f32 v99, -v95, v96, 1.0
	v_fma_f32 v83, -v83, v86, v85
	v_fma_f32 v105, -v101, v102, 1.0
	v_div_fmas_f32 v83, v83, v84, v86
	v_fma_f32 v111, -v107, v108, 1.0
	v_fmac_f32_e32 v90, v93, v90
	v_fmac_f32_e32 v96, v99, v96
	v_fmac_f32_e32 v102, v105, v102
	v_fmac_f32_e32 v108, v111, v108
	v_div_fixup_f32 v65, v65, v64, 1.0
	v_div_fixup_f32 v71, v71, v70, 1.0
	v_div_fixup_f32 v77, v77, v76, 1.0
	v_div_fixup_f32 v83, v83, v82, 1.0
	v_mul_f32_e32 v65, v0, v65
	v_mul_f32_e32 v71, v1, v71
	v_mul_f32_e32 v77, v2, v77
	v_mul_f32_e32 v83, v3, v83
	v_mul_f32_e32 v65, v16, v65
	v_mul_f32_e32 v71, v17, v71
	v_mul_f32_e32 v77, v18, v77
	v_mul_f32_e32 v83, v19, v83
	v_cvt_pk_bf16_f32 v65, v65, v65
	v_cvt_pk_bf16_f32 v71, v71, v71
	v_cvt_pk_bf16_f32 v77, v77, v77
	v_cvt_pk_bf16_f32 v83, v83, v83
	ds_write_b16 v112, v65
	ds_write_b16 v112, v71 offset:64
	ds_write_b16 v112, v77 offset:128
	ds_write_b16 v112, v83 offset:192
	v_div_scale_f32 v91, vcc, 1.0, v88, 1.0
	v_mul_f32_e32 v64, 0xbfb8aa3b, v8
	v_mul_f32_e32 v92, v91, v90
	v_mul_f32_e32 v70, 0xbfb8aa3b, v9
	v_fma_f32 v93, -v89, v92, v91
	v_mul_f32_e32 v76, 0xbfb8aa3b, v10
	v_fmac_f32_e32 v92, v93, v90
	v_mul_f32_e32 v82, 0xbfb8aa3b, v11
	v_fma_f32 v89, -v89, v92, v91
	v_exp_f32_e32 v64, v64
	v_div_fmas_f32 v89, v89, v90, v92
	v_exp_f32_e32 v70, v70
	v_div_scale_f32 v97, vcc, 1.0, v94, 1.0
	v_exp_f32_e32 v76, v76
	v_mul_f32_e32 v98, v97, v96
	v_exp_f32_e32 v82, v82
	v_fma_f32 v99, -v95, v98, v97
	v_add_f32_e32 v64, 1.0, v64
	v_fmac_f32_e32 v98, v99, v96
	v_add_f32_e32 v70, 1.0, v70
	v_fma_f32 v95, -v95, v98, v97
	v_add_f32_e32 v76, 1.0, v76
	v_div_fmas_f32 v95, v95, v96, v98
	v_add_f32_e32 v82, 1.0, v82
	v_div_scale_f32 v103, vcc, 1.0, v100, 1.0
	v_div_scale_f32 v65, s[4:5], v64, v64, 1.0
	v_mul_f32_e32 v104, v103, v102
	v_div_scale_f32 v71, s[4:5], v70, v70, 1.0
	v_fma_f32 v105, -v101, v104, v103
	v_div_scale_f32 v77, s[4:5], v76, v76, 1.0
	v_fmac_f32_e32 v104, v105, v102
	v_div_scale_f32 v83, s[4:5], v82, v82, 1.0
	v_fma_f32 v101, -v101, v104, v103
	v_rcp_f32_e32 v66, v65
	v_div_fmas_f32 v101, v101, v102, v104
	v_rcp_f32_e32 v72, v71
	v_div_scale_f32 v109, vcc, 1.0, v106, 1.0
	v_rcp_f32_e32 v78, v77
	v_mul_f32_e32 v110, v109, v108
	v_rcp_f32_e32 v84, v83
	v_fma_f32 v111, -v107, v110, v109
	v_fma_f32 v69, -v65, v66, 1.0
	v_fmac_f32_e32 v110, v111, v108
	v_fma_f32 v75, -v71, v72, 1.0
	v_fma_f32 v107, -v107, v110, v109
	v_fma_f32 v81, -v77, v78, 1.0
	v_div_fmas_f32 v107, v107, v108, v110
	v_fma_f32 v87, -v83, v84, 1.0
	v_fmac_f32_e32 v66, v69, v66
	v_fmac_f32_e32 v72, v75, v72
	v_fmac_f32_e32 v78, v81, v78
	v_fmac_f32_e32 v84, v87, v84
	v_div_fixup_f32 v89, v89, v88, 1.0
	v_div_fixup_f32 v95, v95, v94, 1.0
	v_div_fixup_f32 v101, v101, v100, 1.0
	v_div_fixup_f32 v107, v107, v106, 1.0
	v_mul_f32_e32 v89, v4, v89
	v_mul_f32_e32 v95, v5, v95
	v_mul_f32_e32 v101, v6, v101
	v_mul_f32_e32 v107, v7, v107
	v_mul_f32_e32 v89, v20, v89
	v_mul_f32_e32 v95, v21, v95
	v_mul_f32_e32 v101, v22, v101
	v_mul_f32_e32 v107, v23, v107
	v_cvt_pk_bf16_f32 v89, v89, v89
	v_cvt_pk_bf16_f32 v95, v95, v95
	v_cvt_pk_bf16_f32 v101, v101, v101
	v_cvt_pk_bf16_f32 v107, v107, v107
	ds_write_b16 v112, v89 offset:512
	ds_write_b16 v112, v95 offset:576
	ds_write_b16 v112, v101 offset:640
	ds_write_b16 v112, v107 offset:704
	v_div_scale_f32 v67, vcc, 1.0, v64, 1.0
	v_mul_f32_e32 v88, 0xbfb8aa3b, v12
	v_mul_f32_e32 v68, v67, v66
	v_mul_f32_e32 v94, 0xbfb8aa3b, v13
	v_fma_f32 v69, -v65, v68, v67
	v_mul_f32_e32 v100, 0xbfb8aa3b, v14
	v_fmac_f32_e32 v68, v69, v66
	v_mul_f32_e32 v106, 0xbfb8aa3b, v15
	v_fma_f32 v65, -v65, v68, v67
	v_exp_f32_e32 v88, v88
	v_div_fmas_f32 v65, v65, v66, v68
	v_exp_f32_e32 v94, v94
	v_div_scale_f32 v73, vcc, 1.0, v70, 1.0
	v_exp_f32_e32 v100, v100
	v_mul_f32_e32 v74, v73, v72
	v_exp_f32_e32 v106, v106
	v_fma_f32 v75, -v71, v74, v73
	v_add_f32_e32 v88, 1.0, v88
	v_fmac_f32_e32 v74, v75, v72
	v_add_f32_e32 v94, 1.0, v94
	v_fma_f32 v71, -v71, v74, v73
	v_add_f32_e32 v100, 1.0, v100
	v_div_fmas_f32 v71, v71, v72, v74
	v_add_f32_e32 v106, 1.0, v106
	v_div_scale_f32 v79, vcc, 1.0, v76, 1.0
	v_div_scale_f32 v89, s[4:5], v88, v88, 1.0
	v_mul_f32_e32 v80, v79, v78
	v_div_scale_f32 v95, s[4:5], v94, v94, 1.0
	v_fma_f32 v81, -v77, v80, v79
	v_div_scale_f32 v101, s[4:5], v100, v100, 1.0
	v_fmac_f32_e32 v80, v81, v78
	v_div_scale_f32 v107, s[4:5], v106, v106, 1.0
	v_fma_f32 v77, -v77, v80, v79
	v_rcp_f32_e32 v90, v89
	v_div_fmas_f32 v77, v77, v78, v80
	v_rcp_f32_e32 v96, v95
	v_div_scale_f32 v85, vcc, 1.0, v82, 1.0
	v_rcp_f32_e32 v102, v101
	v_mul_f32_e32 v86, v85, v84
	v_rcp_f32_e32 v108, v107
	v_fma_f32 v87, -v83, v86, v85
	v_fma_f32 v93, -v89, v90, 1.0
	v_fmac_f32_e32 v86, v87, v84
	v_fma_f32 v99, -v95, v96, 1.0
	v_fma_f32 v83, -v83, v86, v85
	v_fma_f32 v105, -v101, v102, 1.0
	v_div_fmas_f32 v83, v83, v84, v86
	v_fma_f32 v111, -v107, v108, 1.0
	v_fmac_f32_e32 v90, v93, v90
	v_fmac_f32_e32 v96, v99, v96
	v_fmac_f32_e32 v102, v105, v102
	v_fmac_f32_e32 v108, v111, v108
	v_div_fixup_f32 v65, v65, v64, 1.0
	v_div_fixup_f32 v71, v71, v70, 1.0
	v_div_fixup_f32 v77, v77, v76, 1.0
	v_div_fixup_f32 v83, v83, v82, 1.0
	v_mul_f32_e32 v65, v8, v65
	v_mul_f32_e32 v71, v9, v71
	v_mul_f32_e32 v77, v10, v77
	v_mul_f32_e32 v83, v11, v83
	v_mul_f32_e32 v65, v24, v65
	v_mul_f32_e32 v71, v25, v71
	v_mul_f32_e32 v77, v26, v77
	v_mul_f32_e32 v83, v27, v83
	v_cvt_pk_bf16_f32 v65, v65, v65
	v_cvt_pk_bf16_f32 v71, v71, v71
	v_cvt_pk_bf16_f32 v77, v77, v77
	v_cvt_pk_bf16_f32 v83, v83, v83
	ds_write_b16 v112, v65 offset:1024
	ds_write_b16 v112, v71 offset:1088
	ds_write_b16 v112, v77 offset:1152
	ds_write_b16 v112, v83 offset:1216
	v_div_scale_f32 v91, vcc, 1.0, v88, 1.0
	v_mul_f32_e32 v92, v91, v90
	v_fma_f32 v93, -v89, v92, v91
	v_fmac_f32_e32 v92, v93, v90
	v_fma_f32 v89, -v89, v92, v91
	v_div_fmas_f32 v89, v89, v90, v92
	v_div_scale_f32 v97, vcc, 1.0, v94, 1.0
	v_mul_f32_e32 v98, v97, v96
	v_fma_f32 v99, -v95, v98, v97
	v_fmac_f32_e32 v98, v99, v96
	v_fma_f32 v95, -v95, v98, v97
	v_div_fmas_f32 v95, v95, v96, v98
	v_div_scale_f32 v103, vcc, 1.0, v100, 1.0
	v_mul_f32_e32 v104, v103, v102
	v_fma_f32 v105, -v101, v104, v103
	v_fmac_f32_e32 v104, v105, v102
	v_fma_f32 v101, -v101, v104, v103
	v_div_fmas_f32 v101, v101, v102, v104
	v_div_scale_f32 v109, vcc, 1.0, v106, 1.0
	v_mul_f32_e32 v110, v109, v108
	v_fma_f32 v111, -v107, v110, v109
	v_fmac_f32_e32 v110, v111, v108
	v_fma_f32 v107, -v107, v110, v109
	v_div_fmas_f32 v107, v107, v108, v110
	v_div_fixup_f32 v89, v89, v88, 1.0
	v_div_fixup_f32 v95, v95, v94, 1.0
	v_div_fixup_f32 v101, v101, v100, 1.0
	v_div_fixup_f32 v107, v107, v106, 1.0
	v_mul_f32_e32 v89, v12, v89
	v_mul_f32_e32 v95, v13, v95
	v_mul_f32_e32 v101, v14, v101
	v_mul_f32_e32 v107, v15, v107
	v_mul_f32_e32 v89, v28, v89
	v_mul_f32_e32 v95, v29, v95
	v_mul_f32_e32 v101, v30, v101
	v_mul_f32_e32 v107, v31, v107
	v_cvt_pk_bf16_f32 v89, v89, v89
	v_cvt_pk_bf16_f32 v95, v95, v95
	v_cvt_pk_bf16_f32 v101, v101, v101
	v_cvt_pk_bf16_f32 v107, v107, v107
	ds_write_b16 v112, v89 offset:1536
	ds_write_b16 v112, v95 offset:1600
	ds_write_b16 v112, v101 offset:1664
	ds_write_b16 v112, v107 offset:1728
	ds_read_b128 v[120:123], v113
	ds_read_b128 v[124:127], v113 offset:1024
	s_waitcnt lgkmcnt(0)
	global_store_dwordx4 v114, v[120:123], s[98:99]
	s_add_u32 s98, s98, 0x16000
	s_addc_u32 s99, s99, 0
	global_store_dwordx4 v114, v[124:127], s[98:99]
	s_add_u32 s98, s98, 0x16000
	s_addc_u32 s99, s99, 0
